# gla_C normalisation loop LDS reads software-pipelined (out-of-order hoisting with exact lgkmcnt)
# baseline (speedup 1.0000x reference)
; #define LAS __attribute__((address_space(3)))
; __device__ __forceinline__ float bf2f(unsigned short b) { return __uint_as_float(((unsigned)b) << 16); }
; __device__ __forceinline__ unsigned short f2bf(float f) { return (unsigned short)(cvt_pk_bf16(f, 0.f) & 0xffffu); }
; __device__ void gla_C(const Params& P, int l, int item, LAS unsigned char* lds) {
;     ...
;     __syncthreads();
; #pragma unroll
;     for (int rt = 0; rt < 16; ++rt)
; #pragma unroll
;         for (int jj = 0; jj < 4; ++jj) { const int t = rt * 16 + 4 * g + jj; float tot = 0.f;
; #pragma unroll
;             for (int ww = 0; ww < 8; ++ww) tot += SSQ[ww * 256 + t];
;             const float rs = rsqrtf(tot * (1.0f / 128.0f) + EPS);
;             const float gt = bf2f(*(const LAS unsigned short*)(GTL + t * 264 + (16 * w + c) * 2));
;             *(LAS unsigned short*)(OT + t * 272 + (16 * w + c) * 2) = f2bf(O[rt][jj] * rs * ng * (gt * __builtin_amdgcn_rcpf(1.0f + __expf(-gt)))); }
.LBB0_372:
	s_or_b64 exec, exec, s[0:1]
	v_lshl_add_u32 v66, v102, 2, 0
	v_add_u32_e32 v158, 4, v66
	v_add_u32_e32 v159, 8, v66
	v_add_u32_e32 v160, 12, v66
	v_add_u32_e32 v161, 64, v66
	v_add_u32_e32 v162, 0x44, v66
	v_add_u32_e32 v163, 0x48, v66
	v_add_u32_e32 v164, 0x4c, v66
	v_add_u32_e32 v165, 0x80, v66
	v_add_u32_e32 v244, 0x84, v66
	v_add_u32_e32 v245, 0x88, v66
	v_add_u32_e32 v246, 0x8c, v66
	v_add_u32_e32 v247, 0xc0, v66
	v_add_u32_e32 v248, 0xc4, v66
	v_add_u32_e32 v249, 0xc8, v66
	v_add_u32_e32 v236, 0xcc, v66
	s_waitcnt lgkmcnt(0)
	s_barrier
	ds_read2st64_b32 v[116:117], v66 offset1:4
	ds_read2st64_b32 v[118:119], v66 offset0:8 offset1:12
	ds_read2st64_b32 v[120:121], v66 offset0:16 offset1:20
	ds_read2st64_b32 v[122:123], v66 offset0:24 offset1:28
	ds_read2st64_b32 v[124:125], v158 offset1:4
	ds_read2st64_b32 v[126:127], v158 offset0:8 offset1:12
	ds_read2st64_b32 v[128:129], v158 offset0:16 offset1:20
	ds_read2st64_b32 v[130:131], v158 offset0:24 offset1:28
	s_nop 0
	ds_read2st64_b32 v[132:133], v159 offset1:4
	v_readlane_b32 s0, v255, 12
	v_lshlrev_b32_e32 v194, 4, v97
	s_waitcnt lgkmcnt(8)
	v_add_f32_e32 v67, 0, v116
	v_add_f32_e32 v67, v67, v117
	ds_read2st64_b32 v[116:117], v159 offset0:8 offset1:12
	s_waitcnt lgkmcnt(8)
	v_add_f32_e32 v67, v67, v118
	v_add_f32_e32 v67, v67, v119
	s_waitcnt lgkmcnt(7)
	v_add_f32_e32 v67, v67, v120
	v_add_u32_e32 v74, s0, v100
	v_add_f32_e32 v67, v67, v121
	s_movk_i32 s0, 0x420
	s_waitcnt lgkmcnt(6)
	v_add_f32_e32 v67, v67, v122
	v_mad_u32_u24 v68, v157, s0, v74
	ds_read_u16 v243, v68
	ds_read2st64_b32 v[118:119], v159 offset0:16 offset1:20
	v_add_f32_e32 v67, v67, v123
	v_fmamk_f32 v67, v67, 0x3c000000, v1
	v_mul_f32_e32 v69, 0x4b800000, v67
	v_cmp_gt_f32_e32 vcc, s33, v67
	s_waitcnt lgkmcnt(1)
	v_lshlrev_b32_e32 v68, 16, v243
	s_lshl_b32 s20, s31, 1
	v_cndmask_b32_e32 v67, v67, v69, vcc
	v_mul_f32_e32 v69, 0xbfb8aa3b, v68
	v_exp_f32_e32 v69, v69
	v_rsq_f32_e32 v67, v67
	s_add_i32 s45, s45, s94
	s_add_i32 s44, s44, s79
	v_add_f32_e32 v69, 1.0, v69
	v_rcp_f32_e32 v69, v69
	v_mul_f32_e32 v70, 0x45800000, v67
	v_cndmask_b32_e32 v67, v67, v70, vcc
	v_mul_f32_e32 v62, v62, v67
	v_mul_f32_e32 v62, v99, v62
	v_mul_f32_e32 v67, v69, v68
	v_mul_f32_e32 v62, v67, v62
	s_nop 0
	v_cvt_pk_bf16_f32 v62, v62, v195
	ds_read2st64_b32 v[120:121], v159 offset0:24 offset1:28
	v_mul_u32_u24_e32 v70, 0x440, v157
	v_add_u32_e32 v70, v95, v70
	ds_write_b16 v70, v62 offset:8192
	s_nop 0
	ds_read2st64_b32 v[122:123], v160 offset1:4
	s_waitcnt lgkmcnt(4)
	v_add_f32_e32 v62, 0, v124
	v_add_f32_e32 v62, v62, v125
	ds_read2st64_b32 v[124:125], v160 offset0:8 offset1:12
	s_waitcnt lgkmcnt(2)
	v_add_f32_e32 v62, v62, v126
	v_add_f32_e32 v62, v62, v127
	s_waitcnt lgkmcnt(2)
	v_add_f32_e32 v62, v62, v128
	v_add_f32_e32 v62, v62, v129
	s_waitcnt lgkmcnt(2)
	v_add_f32_e32 v62, v62, v130
	v_add_f32_e32 v62, v62, v131
	v_fmamk_f32 v68, v62, 0x3c000000, v1
	v_mad_u32_u24 v62, v96, s9, v74
	ds_read_u16 v243, v62
	ds_read_u16 v242, v62 offset:264
	ds_read2st64_b32 v[126:127], v160 offset0:16 offset1:20
	v_mul_f32_e32 v70, 0x4b800000, v68
	v_cmp_gt_f32_e32 vcc, s33, v68
	s_cmpk_gt_i32 s45, 0xff
	s_waitcnt lgkmcnt(2)
	v_lshlrev_b32_e32 v69, 16, v243
	v_cndmask_b32_e32 v68, v68, v70, vcc
	v_mul_f32_e32 v70, 0xbfb8aa3b, v69
	v_exp_f32_e32 v70, v70
	v_rsq_f32_e32 v68, v68
	v_add_f32_e32 v70, 1.0, v70
	v_rcp_f32_e32 v70, v70
	v_mul_f32_e32 v71, 0x45800000, v68
	v_cndmask_b32_e32 v68, v68, v71, vcc
	v_mul_f32_e32 v63, v63, v68
	v_mul_f32_e32 v63, v99, v63
	v_mul_f32_e32 v68, v70, v69
	v_mul_f32_e32 v63, v68, v63
	v_cvt_pk_bf16_f32 v69, v63, v195
	s_nop 0
	ds_read2st64_b32 v[128:129], v160 offset0:24 offset1:28
	ds_read_u16 v243, v62 offset:528
	v_mul_u32_u24_e32 v68, 0x110, v96
	v_add_u32_e32 v68, v95, v68
	ds_read2st64_b32 v[130:131], v161 offset1:4
	ds_write_b16 v68, v69 offset:8192
	s_waitcnt lgkmcnt(6)
	v_add_f32_e32 v69, 0, v132
	v_add_f32_e32 v69, v69, v133
	ds_read2st64_b32 v[132:133], v161 offset0:8 offset1:12
	s_waitcnt lgkmcnt(7)
	v_add_f32_e32 v69, v69, v116
	v_add_f32_e32 v69, v69, v117
	s_waitcnt lgkmcnt(7)
	v_add_f32_e32 v69, v69, v118
	v_add_f32_e32 v69, v69, v119
	s_waitcnt lgkmcnt(1)
	v_add_f32_e32 v69, v69, v120
	ds_read2st64_b32 v[116:117], v161 offset0:16 offset1:20
	v_add_f32_e32 v69, v69, v121
	v_fmamk_f32 v69, v69, 0x3c000000, v1
	v_mul_f32_e32 v71, 0x4b800000, v69
	v_cmp_gt_f32_e32 vcc, s33, v69
	s_waitcnt lgkmcnt(2)
	v_lshlrev_b32_e32 v70, 16, v242
	v_cndmask_b32_e32 v69, v69, v71, vcc
	v_mul_f32_e32 v71, 0xbfb8aa3b, v70
	v_exp_f32_e32 v71, v71
	v_rsq_f32_e32 v69, v69
	v_add_f32_e32 v71, 1.0, v71
	v_rcp_f32_e32 v71, v71
	v_mul_f32_e32 v72, 0x45800000, v69
	v_cndmask_b32_e32 v69, v69, v72, vcc
	v_mul_f32_e32 v64, v64, v69
	v_mul_f32_e32 v64, v99, v64
	v_mul_f32_e32 v69, v71, v70
	v_mul_f32_e32 v64, v69, v64
	v_cvt_pk_bf16_f32 v69, v64, v195
	s_nop 0
	ds_read2st64_b32 v[118:119], v161 offset0:24 offset1:28
	ds_read_u16 v242, v62 offset:3960
	ds_read2st64_b32 v[120:121], v162 offset1:4
	ds_write_b16 v68, v69 offset:8464
	s_waitcnt lgkmcnt(6)
	v_add_f32_e32 v69, 0, v122
	v_add_f32_e32 v69, v69, v123
	ds_read2st64_b32 v[122:123], v162 offset0:8 offset1:12
	s_waitcnt lgkmcnt(7)
	v_add_f32_e32 v69, v69, v124
	v_add_f32_e32 v69, v69, v125
	s_waitcnt lgkmcnt(7)
	v_add_f32_e32 v69, v69, v126
	v_add_f32_e32 v69, v69, v127
	s_waitcnt lgkmcnt(1)
	v_add_f32_e32 v69, v69, v128
	ds_read2st64_b32 v[124:125], v162 offset0:16 offset1:20
	v_add_f32_e32 v69, v69, v129
	v_fmamk_f32 v69, v69, 0x3c000000, v1
	v_mul_f32_e32 v71, 0x4b800000, v69
	v_cmp_gt_f32_e32 vcc, s33, v69
	s_waitcnt lgkmcnt(2)
; #define LAS __attribute__((address_space(3)))
; __device__ __forceinline__ float bf2f(unsigned short b) { return __uint_as_float(((unsigned)b) << 16); }
; __device__ __forceinline__ unsigned short f2bf(float f) { return (unsigned short)(cvt_pk_bf16(f, 0.f) & 0xffffu); }
; __device__ void gla_C(const Params& P, int l, int item, LAS unsigned char* lds) {
;     ...
;     for (int rt = 0; rt < 16; ++rt)
; #pragma unroll
;         for (int jj = 0; jj < 4; ++jj) { const int t = rt * 16 + 4 * g + jj; float tot = 0.f;
; #pragma unroll
;             for (int ww = 0; ww < 8; ++ww) tot += SSQ[ww * 256 + t];
;             const float rs = rsqrtf(tot * (1.0f / 128.0f) + EPS);
;             const float gt = bf2f(*(const LAS unsigned short*)(GTL + t * 264 + (16 * w + c) * 2));
;             *(LAS unsigned short*)(OT + t * 272 + (16 * w + c) * 2) = f2bf(O[rt][jj] * rs * ng * (gt * __builtin_amdgcn_rcpf(1.0f + __expf(-gt)))); }
	v_lshlrev_b32_e32 v70, 16, v243
	v_cndmask_b32_e32 v69, v69, v71, vcc
	v_mul_f32_e32 v71, 0xbfb8aa3b, v70
	v_exp_f32_e32 v71, v71
	v_rsq_f32_e32 v69, v69
	v_add_f32_e32 v71, 1.0, v71
	v_rcp_f32_e32 v71, v71
	v_mul_f32_e32 v72, 0x45800000, v69
	v_cndmask_b32_e32 v69, v69, v72, vcc
	v_mul_f32_e32 v65, v65, v69
	v_mul_f32_e32 v65, v99, v65
	v_mul_f32_e32 v69, v71, v70
	v_mul_f32_e32 v65, v69, v65
	v_cvt_pk_bf16_f32 v69, v65, v195
	s_nop 0
	ds_read2st64_b32 v[126:127], v162 offset0:24 offset1:28
	ds_read_u16 v243, v62 offset:4224
	ds_read2st64_b32 v[128:129], v163 offset1:4
	ds_write_b16 v68, v69 offset:8736
	s_waitcnt lgkmcnt(6)
	v_add_f32_e32 v69, 0, v130
	v_add_f32_e32 v69, v69, v131
	ds_read2st64_b32 v[130:131], v163 offset0:8 offset1:12
	s_waitcnt lgkmcnt(7)
	v_add_f32_e32 v69, v69, v132
	v_add_f32_e32 v69, v69, v133
	s_waitcnt lgkmcnt(7)
	v_add_f32_e32 v69, v69, v116
	v_add_f32_e32 v69, v69, v117
	s_waitcnt lgkmcnt(1)
	v_add_f32_e32 v69, v69, v118
	ds_read2st64_b32 v[116:117], v163 offset0:16 offset1:20
	v_add_f32_e32 v69, v69, v119
	v_fmamk_f32 v69, v69, 0x3c000000, v1
	v_mul_f32_e32 v71, 0x4b800000, v69
	v_cmp_gt_f32_e32 vcc, s33, v69
	s_waitcnt lgkmcnt(2)
	v_lshlrev_b32_e32 v70, 16, v242
	v_cndmask_b32_e32 v69, v69, v71, vcc
	v_mul_f32_e32 v71, 0xbfb8aa3b, v70
	v_exp_f32_e32 v71, v71
	v_rsq_f32_e32 v69, v69
	v_add_f32_e32 v71, 1.0, v71
	v_rcp_f32_e32 v71, v71
	v_mul_f32_e32 v72, 0x45800000, v69
	v_cndmask_b32_e32 v69, v69, v72, vcc
	v_mul_f32_e32 v58, v58, v69
	v_mul_f32_e32 v58, v99, v58
	v_mul_f32_e32 v69, v71, v70
	v_mul_f32_e32 v58, v69, v58
	v_cvt_pk_bf16_f32 v69, v58, v195
	s_nop 0
	ds_read2st64_b32 v[118:119], v163 offset0:24 offset1:28
	ds_read_u16 v242, v62 offset:4488
	ds_read2st64_b32 v[132:133], v164 offset1:4
	ds_write_b16 v68, v69 offset:12272
	s_waitcnt lgkmcnt(6)
	v_add_f32_e32 v69, 0, v120
	v_add_f32_e32 v69, v69, v121
	ds_read2st64_b32 v[120:121], v164 offset0:8 offset1:12
	s_waitcnt lgkmcnt(7)
	v_add_f32_e32 v69, v69, v122
	v_add_f32_e32 v69, v69, v123
	s_waitcnt lgkmcnt(7)
	v_add_f32_e32 v69, v69, v124
	v_add_f32_e32 v69, v69, v125
	s_waitcnt lgkmcnt(1)
	v_add_f32_e32 v69, v69, v126
	ds_read2st64_b32 v[122:123], v164 offset0:16 offset1:20
	v_add_f32_e32 v69, v69, v127
	v_fmamk_f32 v69, v69, 0x3c000000, v1
	v_mul_f32_e32 v71, 0x4b800000, v69
	v_cmp_gt_f32_e32 vcc, s33, v69
	s_waitcnt lgkmcnt(2)
	v_lshlrev_b32_e32 v70, 16, v243
	v_cndmask_b32_e32 v69, v69, v71, vcc
	v_mul_f32_e32 v71, 0xbfb8aa3b, v70
	v_exp_f32_e32 v71, v71
	v_rsq_f32_e32 v69, v69
	v_add_f32_e32 v71, 1.0, v71
	v_rcp_f32_e32 v71, v71
	v_mul_f32_e32 v72, 0x45800000, v69
	v_cndmask_b32_e32 v69, v69, v72, vcc
	v_mul_f32_e32 v59, v59, v69
	v_mul_f32_e32 v59, v99, v59
	v_mul_f32_e32 v69, v71, v70
	v_mul_f32_e32 v59, v69, v59
	v_cvt_pk_bf16_f32 v69, v59, v195
	s_nop 0
	ds_read2st64_b32 v[124:125], v164 offset0:24 offset1:28
	ds_write_b16 v68, v69 offset:12544
	ds_read_u16 v243, v62 offset:4752
	ds_read2st64_b32 v[126:127], v165 offset1:4
	s_waitcnt lgkmcnt(6)
	v_add_f32_e32 v70, 0, v128
	v_add_f32_e32 v74, v70, v129
	ds_read2st64_b32 v[128:129], v165 offset0:8 offset1:12
	s_waitcnt lgkmcnt(3)
	v_add_f32_e32 v68, v74, v130
	v_add_f32_e32 v68, v68, v131
	s_waitcnt lgkmcnt(3)
	v_add_f32_e32 v68, v68, v116
	ds_read2st64_b32 v[130:131], v165 offset0:16 offset1:20
	v_add_f32_e32 v68, v68, v117
	s_waitcnt lgkmcnt(4)
	v_add_f32_e32 v68, v68, v118
	v_add_f32_e32 v68, v68, v119
	v_fmamk_f32 v68, v68, 0x3c000000, v1
	v_mul_f32_e32 v70, 0x4b800000, v68
	v_cmp_gt_f32_e32 vcc, s33, v68
	s_waitcnt lgkmcnt(4)
	v_lshlrev_b32_e32 v69, 16, v242
	v_cndmask_b32_e32 v68, v68, v70, vcc
	v_mul_f32_e32 v70, 0xbfb8aa3b, v69
	v_exp_f32_e32 v70, v70
	v_rsq_f32_e32 v68, v68
	v_add_f32_e32 v70, 1.0, v70
	v_rcp_f32_e32 v70, v70
	v_mul_f32_e32 v71, 0x45800000, v68
	v_cndmask_b32_e32 v68, v68, v71, vcc
	v_mul_f32_e32 v60, v60, v68
	v_mul_f32_e32 v60, v99, v60
	v_mul_f32_e32 v68, v70, v69
	v_mul_f32_e32 v60, v68, v60
	v_cvt_pk_bf16_f32 v70, v60, v195
	s_nop 0
	ds_read2st64_b32 v[116:117], v165 offset0:24 offset1:28
	ds_write_b16 v94, v70 offset:8192
	ds_read_u16 v242, v62 offset:8184
	ds_read2st64_b32 v[118:119], v244 offset1:4
	s_waitcnt lgkmcnt(8)
	v_add_f32_e32 v68, 0, v132
	v_add_f32_e32 v74, v68, v133
	ds_read2st64_b32 v[132:133], v244 offset0:8 offset1:12
	s_waitcnt lgkmcnt(3)
	v_add_f32_e32 v70, v74, v120
	v_add_f32_e32 v70, v70, v121
	s_waitcnt lgkmcnt(3)
	v_add_f32_e32 v70, v70, v122
	v_add_f32_e32 v70, v70, v123
	s_waitcnt lgkmcnt(3)
	v_add_f32_e32 v68, v70, v124
	v_add_f32_e32 v68, v68, v125
	ds_read2st64_b32 v[120:121], v244 offset0:16 offset1:20
	v_fmamk_f32 v68, v68, 0x3c000000, v1
	v_mul_f32_e32 v70, 0x4b800000, v68
	v_cmp_gt_f32_e32 vcc, s33, v68
	s_waitcnt lgkmcnt(4)
	v_lshlrev_b32_e32 v69, 16, v243
	v_cndmask_b32_e32 v68, v68, v70, vcc
	v_mul_f32_e32 v70, 0xbfb8aa3b, v69
	v_exp_f32_e32 v70, v70
	v_rsq_f32_e32 v68, v68
	v_add_f32_e32 v70, 1.0, v70
	v_rcp_f32_e32 v70, v70
	v_mul_f32_e32 v71, 0x45800000, v68
	v_cndmask_b32_e32 v68, v68, v71, vcc
	v_mul_f32_e32 v61, v61, v68
	v_mul_f32_e32 v61, v99, v61
	v_mul_f32_e32 v68, v70, v69
	v_mul_f32_e32 v61, v68, v61
	v_cvt_pk_bf16_f32 v70, v61, v195
	s_nop 0
	ds_read_u16 v243, v62 offset:8448
	ds_write_b16 v94, v70 offset:8464
	ds_read2st64_b32 v[122:123], v244 offset0:24 offset1:28
	ds_read2st64_b32 v[124:125], v245 offset1:4
	s_waitcnt lgkmcnt(8)
	v_add_f32_e32 v68, 0, v126
	v_add_f32_e32 v74, v68, v127
	ds_read2st64_b32 v[126:127], v245 offset0:8 offset1:12
	s_waitcnt lgkmcnt(3)
	v_add_f32_e32 v70, v74, v128
	v_add_f32_e32 v70, v70, v129
	s_waitcnt lgkmcnt(3)
	v_add_f32_e32 v70, v70, v130
	v_add_f32_e32 v70, v70, v131
	s_waitcnt lgkmcnt(3)
; #define LAS __attribute__((address_space(3)))
; __device__ __forceinline__ float bf2f(unsigned short b) { return __uint_as_float(((unsigned)b) << 16); }
; __device__ __forceinline__ unsigned short f2bf(float f) { return (unsigned short)(cvt_pk_bf16(f, 0.f) & 0xffffu); }
; __device__ void gla_C(const Params& P, int l, int item, LAS unsigned char* lds) {
;     ...
;     for (int rt = 0; rt < 16; ++rt)
; #pragma unroll
;         for (int jj = 0; jj < 4; ++jj) { const int t = rt * 16 + 4 * g + jj; float tot = 0.f;
; #pragma unroll
;             for (int ww = 0; ww < 8; ++ww) tot += SSQ[ww * 256 + t];
;             const float rs = rsqrtf(tot * (1.0f / 128.0f) + EPS);
;             const float gt = bf2f(*(const LAS unsigned short*)(GTL + t * 264 + (16 * w + c) * 2));
;             *(LAS unsigned short*)(OT + t * 272 + (16 * w + c) * 2) = f2bf(O[rt][jj] * rs * ng * (gt * __builtin_amdgcn_rcpf(1.0f + __expf(-gt)))); }
	v_add_f32_e32 v68, v70, v116
	v_add_f32_e32 v68, v68, v117
	ds_read2st64_b32 v[116:117], v245 offset0:16 offset1:20
	v_fmamk_f32 v68, v68, 0x3c000000, v1
	v_mul_f32_e32 v70, 0x4b800000, v68
	v_cmp_gt_f32_e32 vcc, s33, v68
	s_waitcnt lgkmcnt(4)
	v_lshlrev_b32_e32 v69, 16, v242
	v_cndmask_b32_e32 v68, v68, v70, vcc
	v_mul_f32_e32 v70, 0xbfb8aa3b, v69
	v_exp_f32_e32 v70, v70
	v_rsq_f32_e32 v68, v68
	v_add_f32_e32 v70, 1.0, v70
	v_rcp_f32_e32 v70, v70
	v_mul_f32_e32 v71, 0x45800000, v68
	v_cndmask_b32_e32 v68, v68, v71, vcc
	v_mul_f32_e32 v54, v54, v68
	v_mul_f32_e32 v54, v99, v54
	v_mul_f32_e32 v68, v70, v69
	v_mul_f32_e32 v54, v68, v54
	s_nop 0
	v_cvt_pk_bf16_f32 v54, v54, v195
	ds_read2st64_b32 v[128:129], v245 offset0:24 offset1:28
	ds_read_u16 v242, v62 offset:8712
	ds_read2st64_b32 v[130:131], v246 offset1:4
	ds_write_b16 v94, v54 offset:12000
	ds_read2st64_b32 v[134:135], v246 offset0:8 offset1:12
	s_waitcnt lgkmcnt(9)
	v_add_f32_e32 v54, 0, v118
	v_add_f32_e32 v54, v54, v119
	ds_read2st64_b32 v[118:119], v246 offset0:16 offset1:20
	s_waitcnt lgkmcnt(10)
	v_add_f32_e32 v54, v54, v132
	v_add_f32_e32 v54, v54, v133
	s_waitcnt lgkmcnt(10)
	v_add_f32_e32 v54, v54, v120
	v_add_f32_e32 v54, v54, v121
	s_waitcnt lgkmcnt(2)
	v_add_f32_e32 v54, v54, v122
	v_add_f32_e32 v54, v54, v123
	v_fmamk_f32 v54, v54, 0x3c000000, v1
	v_mul_f32_e32 v70, 0x4b800000, v54
	v_cmp_gt_f32_e32 vcc, s33, v54
	v_lshlrev_b32_e32 v69, 16, v243
	s_nop 0
	v_cndmask_b32_e32 v54, v54, v70, vcc
	v_mul_f32_e32 v70, 0xbfb8aa3b, v69
	v_exp_f32_e32 v70, v70
	v_rsq_f32_e32 v54, v54
	v_add_f32_e32 v70, 1.0, v70
	v_rcp_f32_e32 v70, v70
	v_mul_f32_e32 v71, 0x45800000, v54
	v_cndmask_b32_e32 v54, v54, v71, vcc
	v_mul_f32_e32 v54, v55, v54
	v_mul_f32_e32 v54, v99, v54
	v_mul_f32_e32 v55, v70, v69
	v_mul_f32_e32 v54, v55, v54
	s_nop 0
	v_cvt_pk_bf16_f32 v70, v54, v195
	ds_read2st64_b32 v[120:121], v246 offset0:24 offset1:28
	ds_write_b16 v94, v70 offset:12272
	ds_read_u16 v243, v62 offset:8976
	ds_read2st64_b32 v[122:123], v247 offset1:4
	s_waitcnt lgkmcnt(6)
	v_add_f32_e32 v54, 0, v124
	v_add_f32_e32 v74, v54, v125
	ds_read2st64_b32 v[124:125], v247 offset0:8 offset1:12
	s_waitcnt lgkmcnt(3)
	v_add_f32_e32 v70, v74, v126
	v_add_f32_e32 v70, v70, v127
	s_waitcnt lgkmcnt(3)
	v_add_f32_e32 v70, v70, v116
	v_add_f32_e32 v70, v70, v117
	s_waitcnt lgkmcnt(3)
	v_add_f32_e32 v54, v70, v128
	v_add_f32_e32 v54, v54, v129
	ds_read2st64_b32 v[116:117], v247 offset0:16 offset1:20
	v_fmamk_f32 v54, v54, 0x3c000000, v1
	v_mul_f32_e32 v70, 0x4b800000, v54
	v_cmp_gt_f32_e32 vcc, s33, v54
	s_waitcnt lgkmcnt(4)
	v_lshlrev_b32_e32 v55, 16, v242
	v_cndmask_b32_e32 v54, v54, v70, vcc
	v_mul_f32_e32 v70, 0xbfb8aa3b, v55
	v_exp_f32_e32 v70, v70
	v_rsq_f32_e32 v54, v54
	v_add_f32_e32 v70, 1.0, v70
	v_rcp_f32_e32 v70, v70
	v_mul_f32_e32 v71, 0x45800000, v54
	v_cndmask_b32_e32 v54, v54, v71, vcc
	v_mul_f32_e32 v54, v56, v54
	v_mul_f32_e32 v54, v99, v54
	v_mul_f32_e32 v55, v70, v55
	v_mul_f32_e32 v54, v55, v54
	s_nop 0
	v_cvt_pk_bf16_f32 v70, v54, v195
	ds_read_u16 v242, v62 offset:12408
	ds_write_b16 v94, v70 offset:12544
	ds_read2st64_b32 v[126:127], v247 offset0:24 offset1:28
	ds_read2st64_b32 v[128:129], v248 offset1:4
	s_waitcnt lgkmcnt(8)
	v_add_f32_e32 v54, 0, v130
	v_add_f32_e32 v74, v54, v131
	ds_read2st64_b32 v[130:131], v248 offset0:8 offset1:12
	s_waitcnt lgkmcnt(3)
	v_add_f32_e32 v70, v74, v134
	v_add_f32_e32 v70, v70, v135
	s_waitcnt lgkmcnt(3)
	v_add_f32_e32 v70, v70, v118
	v_add_f32_e32 v70, v70, v119
	s_waitcnt lgkmcnt(3)
	v_add_f32_e32 v54, v70, v120
	v_add_f32_e32 v54, v54, v121
	ds_read2st64_b32 v[118:119], v248 offset0:16 offset1:20
	v_fmamk_f32 v54, v54, 0x3c000000, v1
	v_mul_f32_e32 v70, 0x4b800000, v54
	v_cmp_gt_f32_e32 vcc, s33, v54
	s_waitcnt lgkmcnt(4)
	v_lshlrev_b32_e32 v55, 16, v243
	v_cndmask_b32_e32 v54, v54, v70, vcc
	v_mul_f32_e32 v70, 0xbfb8aa3b, v55
	v_exp_f32_e32 v70, v70
	v_rsq_f32_e32 v54, v54
	v_add_f32_e32 v70, 1.0, v70
	v_rcp_f32_e32 v70, v70
	v_mul_f32_e32 v71, 0x45800000, v54
	v_cndmask_b32_e32 v54, v54, v71, vcc
	v_mul_f32_e32 v54, v57, v54
	v_mul_f32_e32 v54, v99, v54
	v_mul_f32_e32 v55, v70, v55
	v_mul_f32_e32 v54, v55, v54
	s_nop 0
	v_cvt_pk_bf16_f32 v54, v54, v195
	ds_read_u16 v243, v62 offset:12672
	ds_read2st64_b32 v[120:121], v248 offset0:24 offset1:28
	ds_read2st64_b32 v[132:133], v249 offset1:4
	ds_write_b16 v93, v54 offset:8192
	ds_read2st64_b32 v[134:135], v249 offset0:8 offset1:12
	s_waitcnt lgkmcnt(9)
	v_add_f32_e32 v54, 0, v122
	v_add_f32_e32 v54, v54, v123
	ds_read2st64_b32 v[122:123], v249 offset0:16 offset1:20
	s_waitcnt lgkmcnt(10)
	v_add_f32_e32 v54, v54, v124
	v_add_f32_e32 v54, v54, v125
	s_waitcnt lgkmcnt(10)
	v_add_f32_e32 v54, v54, v116
	v_add_f32_e32 v54, v54, v117
	s_waitcnt lgkmcnt(2)
	v_add_f32_e32 v54, v54, v126
	v_add_f32_e32 v54, v54, v127
	v_fmamk_f32 v54, v54, 0x3c000000, v1
	v_mul_f32_e32 v70, 0x4b800000, v54
	v_cmp_gt_f32_e32 vcc, s33, v54
	v_lshlrev_b32_e32 v57, 16, v242
	s_nop 0
	v_cndmask_b32_e32 v54, v54, v70, vcc
	v_mul_f32_e32 v70, 0xbfb8aa3b, v57
	v_exp_f32_e32 v70, v70
	v_rsq_f32_e32 v54, v54
	v_add_f32_e32 v70, 1.0, v70
	v_rcp_f32_e32 v70, v70
	v_mul_f32_e32 v71, 0x45800000, v54
	v_cndmask_b32_e32 v54, v54, v71, vcc
	v_mul_f32_e32 v50, v50, v54
	v_mul_f32_e32 v50, v99, v50
	v_mul_f32_e32 v54, v70, v57
	v_mul_f32_e32 v50, v54, v50
	s_nop 0
	v_cvt_pk_bf16_f32 v50, v50, v195
	ds_read_u16 v242, v62 offset:12936
	ds_read2st64_b32 v[116:117], v249 offset0:24 offset1:28
	ds_read2st64_b32 v[124:125], v236 offset1:4
	ds_write_b16 v93, v50 offset:11728
	ds_read2st64_b32 v[126:127], v236 offset0:8 offset1:12
	s_waitcnt lgkmcnt(7)
; #define LAS __attribute__((address_space(3)))
; __device__ __forceinline__ float bf2f(unsigned short b) { return __uint_as_float(((unsigned)b) << 16); }
; __device__ __forceinline__ unsigned short f2bf(float f) { return (unsigned short)(cvt_pk_bf16(f, 0.f) & 0xffffu); }
; __device__ void gla_C(const Params& P, int l, int item, LAS unsigned char* lds) {
;     ...
;     for (int rt = 0; rt < 16; ++rt)
; #pragma unroll
;         for (int jj = 0; jj < 4; ++jj) { const int t = rt * 16 + 4 * g + jj; float tot = 0.f;
; #pragma unroll
;             for (int ww = 0; ww < 8; ++ww) tot += SSQ[ww * 256 + t];
;             const float rs = rsqrtf(tot * (1.0f / 128.0f) + EPS);
;             const float gt = bf2f(*(const LAS unsigned short*)(GTL + t * 264 + (16 * w + c) * 2));
;             *(LAS unsigned short*)(OT + t * 272 + (16 * w + c) * 2) = f2bf(O[rt][jj] * rs * ng * (gt * __builtin_amdgcn_rcpf(1.0f + __expf(-gt)))); }
	v_add_f32_e32 v50, 0, v128
	v_add_f32_e32 v50, v50, v129
	ds_read2st64_b32 v[128:129], v236 offset0:16 offset1:20
	s_waitcnt lgkmcnt(8)
	v_add_f32_e32 v50, v50, v130
	v_add_f32_e32 v50, v50, v131
	s_waitcnt lgkmcnt(8)
	v_add_f32_e32 v50, v50, v118
	v_add_f32_e32 v50, v50, v119
	s_waitcnt lgkmcnt(2)
	v_add_f32_e32 v50, v50, v120
	v_add_f32_e32 v50, v50, v121
	v_fmamk_f32 v50, v50, 0x3c000000, v1
	v_mul_f32_e32 v70, 0x4b800000, v50
	v_cmp_gt_f32_e32 vcc, s33, v50
	v_lshlrev_b32_e32 v57, 16, v243
	s_nop 0
	v_cndmask_b32_e32 v50, v50, v70, vcc
	v_mul_f32_e32 v70, 0xbfb8aa3b, v57
	v_exp_f32_e32 v70, v70
	v_rsq_f32_e32 v50, v50
	v_add_f32_e32 v70, 1.0, v70
	v_rcp_f32_e32 v70, v70
	v_mul_f32_e32 v71, 0x45800000, v50
	v_cndmask_b32_e32 v50, v50, v71, vcc
	v_mul_f32_e32 v50, v51, v50
	v_mul_f32_e32 v50, v99, v50
	v_mul_f32_e32 v51, v70, v57
	v_mul_f32_e32 v50, v51, v50
	s_nop 0
	v_cvt_pk_bf16_f32 v50, v50, v195
	ds_read_u16 v243, v62 offset:13200
	ds_read2st64_b32 v[118:119], v236 offset0:24 offset1:28
	ds_read2st64_b32 v[120:121], v66 offset0:1 offset1:5
	ds_write_b16 v93, v50 offset:12000
	ds_read2st64_b32 v[130:131], v66 offset0:9 offset1:13
	s_waitcnt lgkmcnt(7)
	v_add_f32_e32 v50, 0, v132
	v_add_f32_e32 v50, v50, v133
	ds_read2st64_b32 v[132:133], v66 offset0:17 offset1:21
	s_waitcnt lgkmcnt(8)
	v_add_f32_e32 v50, v50, v134
	v_add_f32_e32 v50, v50, v135
	s_waitcnt lgkmcnt(8)
	v_add_f32_e32 v50, v50, v122
	v_add_f32_e32 v50, v50, v123
	s_waitcnt lgkmcnt(2)
	v_add_f32_e32 v50, v50, v116
	v_add_f32_e32 v50, v50, v117
	v_fmamk_f32 v50, v50, 0x3c000000, v1
	v_mul_f32_e32 v70, 0x4b800000, v50
	v_cmp_gt_f32_e32 vcc, s33, v50
	v_lshlrev_b32_e32 v57, 16, v242
	s_nop 0
	v_cndmask_b32_e32 v50, v50, v70, vcc
	v_mul_f32_e32 v70, 0xbfb8aa3b, v57
	v_exp_f32_e32 v70, v70
	v_rsq_f32_e32 v50, v50
	v_add_f32_e32 v70, 1.0, v70
	v_rcp_f32_e32 v70, v70
	v_mul_f32_e32 v71, 0x45800000, v50
	v_cndmask_b32_e32 v50, v50, v71, vcc
	v_mul_f32_e32 v50, v52, v50
	v_mul_f32_e32 v50, v99, v50
	v_mul_f32_e32 v52, v70, v57
	v_mul_f32_e32 v50, v52, v50
	v_cvt_pk_bf16_f32 v52, v50, v195
	s_nop 0
	ds_read2st64_b32 v[116:117], v66 offset0:25 offset1:29
	ds_read_u16 v242, v62 offset:16632
	ds_read2st64_b32 v[122:123], v158 offset0:1 offset1:5
	ds_write_b16 v93, v52 offset:12272
	ds_read2st64_b32 v[134:135], v158 offset0:9 offset1:13
	s_waitcnt lgkmcnt(7)
	v_add_f32_e32 v52, 0, v124
	v_add_f32_e32 v52, v52, v125
	ds_read2st64_b32 v[124:125], v158 offset0:17 offset1:21
	s_waitcnt lgkmcnt(8)
	v_add_f32_e32 v52, v52, v126
	v_add_f32_e32 v52, v52, v127
	s_waitcnt lgkmcnt(8)
	v_add_f32_e32 v52, v52, v128
	v_add_f32_e32 v52, v52, v129
	s_waitcnt lgkmcnt(2)
	v_add_f32_e32 v52, v52, v118
	v_add_f32_e32 v52, v52, v119
	v_fmamk_f32 v52, v52, 0x3c000000, v1
	v_mul_f32_e32 v70, 0x4b800000, v52
	v_cmp_gt_f32_e32 vcc, s33, v52
	v_lshlrev_b32_e32 v57, 16, v243
	s_nop 0
	v_cndmask_b32_e32 v52, v52, v70, vcc
	v_mul_f32_e32 v70, 0xbfb8aa3b, v57
	v_exp_f32_e32 v70, v70
	v_rsq_f32_e32 v52, v52
	v_add_f32_e32 v70, 1.0, v70
	v_rcp_f32_e32 v70, v70
	v_mul_f32_e32 v71, 0x45800000, v52
	v_cndmask_b32_e32 v52, v52, v71, vcc
	v_mul_f32_e32 v52, v53, v52
	v_mul_f32_e32 v52, v99, v52
	v_mul_f32_e32 v53, v70, v57
	v_mul_f32_e32 v52, v53, v52
	v_cvt_pk_bf16_f32 v57, v52, v195
	ds_read2st64_b32 v[118:119], v158 offset0:25 offset1:29
	ds_read_u16 v243, v62 offset:16896
	ds_read2st64_b32 v[126:127], v159 offset0:1 offset1:5
	ds_write_b16 v93, v57 offset:12544
	s_waitcnt lgkmcnt(6)
	v_add_f32_e32 v52, 0, v120
	v_add_f32_e32 v57, v52, v121
	ds_read2st64_b32 v[120:121], v159 offset0:9 offset1:13
	s_waitcnt lgkmcnt(7)
	v_add_f32_e32 v57, v57, v130
	v_add_f32_e32 v57, v57, v131
	s_waitcnt lgkmcnt(7)
	v_add_f32_e32 v57, v57, v132
	v_add_f32_e32 v57, v57, v133
	s_waitcnt lgkmcnt(1)
	v_add_f32_e32 v52, v57, v116
	v_add_f32_e32 v52, v52, v117
	ds_read2st64_b32 v[116:117], v159 offset0:17 offset1:21
	v_fmamk_f32 v52, v52, 0x3c000000, v1
	v_mul_f32_e32 v57, 0x4b800000, v52
	v_cmp_gt_f32_e32 vcc, s33, v52
	s_waitcnt lgkmcnt(2)
	v_lshlrev_b32_e32 v53, 16, v242
	v_cndmask_b32_e32 v52, v52, v57, vcc
	v_mul_f32_e32 v57, 0xbfb8aa3b, v53
	v_exp_f32_e32 v57, v57
	v_rsq_f32_e32 v52, v52
	v_add_f32_e32 v57, 1.0, v57
	v_rcp_f32_e32 v57, v57
	v_mul_f32_e32 v70, 0x45800000, v52
	v_cndmask_b32_e32 v52, v52, v70, vcc
	v_mul_f32_e32 v46, v46, v52
	v_mul_f32_e32 v46, v99, v46
	v_mul_f32_e32 v52, v57, v53
	v_mul_f32_e32 v46, v52, v46
	v_cvt_pk_bf16_f32 v46, v46, v195
	ds_read2st64_b32 v[128:129], v159 offset0:25 offset1:29
	ds_read_u16 v242, v62 offset:17160
	ds_read2st64_b32 v[130:131], v160 offset0:1 offset1:5
	ds_write_b16 v92, v46 offset:8192
	s_waitcnt lgkmcnt(6)
	v_add_f32_e32 v46, 0, v122
	v_add_f32_e32 v46, v46, v123
	ds_read2st64_b32 v[122:123], v160 offset0:9 offset1:13
	s_waitcnt lgkmcnt(7)
	v_add_f32_e32 v46, v46, v134
	v_add_f32_e32 v46, v46, v135
	s_waitcnt lgkmcnt(7)
	v_add_f32_e32 v46, v46, v124
	v_add_f32_e32 v46, v46, v125
	s_waitcnt lgkmcnt(1)
	v_add_f32_e32 v46, v46, v118
	ds_read2st64_b32 v[124:125], v160 offset0:17 offset1:21
	v_add_f32_e32 v46, v46, v119
	v_fmamk_f32 v46, v46, 0x3c000000, v1
	v_mul_f32_e32 v53, 0x4b800000, v46
	v_cmp_gt_f32_e32 vcc, s33, v46
	s_waitcnt lgkmcnt(2)
	v_lshlrev_b32_e32 v52, 16, v243
	v_cndmask_b32_e32 v46, v46, v53, vcc
	v_mul_f32_e32 v53, 0xbfb8aa3b, v52
	v_exp_f32_e32 v53, v53
	v_rsq_f32_e32 v46, v46
	v_add_f32_e32 v53, 1.0, v53
	v_rcp_f32_e32 v53, v53
	v_mul_f32_e32 v57, 0x45800000, v46
	v_cndmask_b32_e32 v46, v46, v57, vcc
	v_mul_f32_e32 v46, v47, v46
	v_mul_f32_e32 v46, v99, v46
	v_mul_f32_e32 v47, v53, v52
	v_mul_f32_e32 v46, v47, v46
	v_cvt_pk_bf16_f32 v52, v46, v195
	ds_read2st64_b32 v[118:119], v160 offset0:25 offset1:29
	ds_write_b16 v92, v52 offset:8464
	ds_read_u16 v243, v62 offset:17424
	ds_read2st64_b32 v[132:133], v161 offset0:1 offset1:5
	s_waitcnt lgkmcnt(6)
; #define LAS __attribute__((address_space(3)))
; __device__ __forceinline__ float bf2f(unsigned short b) { return __uint_as_float(((unsigned)b) << 16); }
; __device__ __forceinline__ unsigned short f2bf(float f) { return (unsigned short)(cvt_pk_bf16(f, 0.f) & 0xffffu); }
; __device__ void gla_C(const Params& P, int l, int item, LAS unsigned char* lds) {
;     ...
;     for (int rt = 0; rt < 16; ++rt)
; #pragma unroll
;         for (int jj = 0; jj < 4; ++jj) { const int t = rt * 16 + 4 * g + jj; float tot = 0.f;
; #pragma unroll
;             for (int ww = 0; ww < 8; ++ww) tot += SSQ[ww * 256 + t];
;             const float rs = rsqrtf(tot * (1.0f / 128.0f) + EPS);
;             const float gt = bf2f(*(const LAS unsigned short*)(GTL + t * 264 + (16 * w + c) * 2));
;             *(LAS unsigned short*)(OT + t * 272 + (16 * w + c) * 2) = f2bf(O[rt][jj] * rs * ng * (gt * __builtin_amdgcn_rcpf(1.0f + __expf(-gt)))); }
	v_add_f32_e32 v46, 0, v126
	v_add_f32_e32 v57, v46, v127
	ds_read2st64_b32 v[126:127], v161 offset0:9 offset1:13
	s_waitcnt lgkmcnt(3)
	v_add_f32_e32 v52, v57, v120
	v_add_f32_e32 v52, v52, v121
	s_waitcnt lgkmcnt(3)
	v_add_f32_e32 v52, v52, v116
	v_add_f32_e32 v52, v52, v117
	s_waitcnt lgkmcnt(3)
	v_add_f32_e32 v46, v52, v128
	v_add_f32_e32 v46, v46, v129
	ds_read2st64_b32 v[116:117], v161 offset0:17 offset1:21
	v_fmamk_f32 v46, v46, 0x3c000000, v1
	v_mul_f32_e32 v52, 0x4b800000, v46
	v_cmp_gt_f32_e32 vcc, s33, v46
	s_waitcnt lgkmcnt(4)
	v_lshlrev_b32_e32 v47, 16, v242
	v_cndmask_b32_e32 v46, v46, v52, vcc
	v_mul_f32_e32 v52, 0xbfb8aa3b, v47
	v_exp_f32_e32 v52, v52
	v_rsq_f32_e32 v46, v46
	v_add_f32_e32 v52, 1.0, v52
	v_rcp_f32_e32 v52, v52
	v_mul_f32_e32 v53, 0x45800000, v46
	v_cndmask_b32_e32 v46, v46, v53, vcc
	v_mul_f32_e32 v46, v48, v46
	v_mul_f32_e32 v46, v99, v46
	v_mul_f32_e32 v47, v52, v47
	v_mul_f32_e32 v46, v47, v46
	v_cvt_pk_bf16_f32 v48, v46, v195
	ds_read2st64_b32 v[120:121], v161 offset0:25 offset1:29
	ds_read_u16 v242, v62 offset:20856
	ds_read2st64_b32 v[128:129], v162 offset0:1 offset1:5
	ds_write_b16 v92, v48 offset:8736
	s_waitcnt lgkmcnt(8)
	v_add_f32_e32 v46, 0, v130
	v_add_f32_e32 v48, v46, v131
	ds_read2st64_b32 v[130:131], v162 offset0:9 offset1:13
	s_waitcnt lgkmcnt(9)
	v_add_f32_e32 v48, v48, v122
	v_add_f32_e32 v48, v48, v123
	s_waitcnt lgkmcnt(9)
	v_add_f32_e32 v48, v48, v124
	v_add_f32_e32 v48, v48, v125
	s_waitcnt lgkmcnt(1)
	v_add_f32_e32 v46, v48, v118
	v_add_f32_e32 v46, v46, v119
	ds_read2st64_b32 v[118:119], v162 offset0:17 offset1:21
	v_fmamk_f32 v46, v46, 0x3c000000, v1
	v_mul_f32_e32 v48, 0x4b800000, v46
	v_cmp_gt_f32_e32 vcc, s33, v46
	s_waitcnt lgkmcnt(2)
	v_lshlrev_b32_e32 v47, 16, v243
	v_cndmask_b32_e32 v46, v46, v48, vcc
	v_mul_f32_e32 v48, 0xbfb8aa3b, v47
	v_exp_f32_e32 v48, v48
	v_rsq_f32_e32 v46, v46
	v_add_f32_e32 v48, 1.0, v48
	v_rcp_f32_e32 v48, v48
	v_mul_f32_e32 v52, 0x45800000, v46
	v_cndmask_b32_e32 v46, v46, v52, vcc
	v_mul_f32_e32 v46, v49, v46
	v_mul_f32_e32 v46, v99, v46
	v_mul_f32_e32 v47, v48, v47
	v_mul_f32_e32 v46, v47, v46
	v_cvt_pk_bf16_f32 v48, v46, v195
	ds_read2st64_b32 v[122:123], v162 offset0:25 offset1:29
	ds_write_b16 v92, v48 offset:9008
	ds_read_u16 v243, v62 offset:21120
	ds_read2st64_b32 v[124:125], v163 offset0:1 offset1:5
	s_waitcnt lgkmcnt(6)
	v_add_f32_e32 v46, 0, v132
	v_add_f32_e32 v57, v46, v133
	ds_read2st64_b32 v[132:133], v163 offset0:9 offset1:13
	s_waitcnt lgkmcnt(3)
	v_add_f32_e32 v48, v57, v126
	v_add_f32_e32 v48, v48, v127
	s_waitcnt lgkmcnt(3)
	v_add_f32_e32 v48, v48, v116
	v_add_f32_e32 v48, v48, v117
	s_waitcnt lgkmcnt(3)
	v_add_f32_e32 v46, v48, v120
	v_add_f32_e32 v46, v46, v121
	ds_read2st64_b32 v[116:117], v163 offset0:17 offset1:21
	v_fmamk_f32 v46, v46, 0x3c000000, v1
	v_mul_f32_e32 v48, 0x4b800000, v46
	v_cmp_gt_f32_e32 vcc, s33, v46
	s_waitcnt lgkmcnt(4)
	v_lshlrev_b32_e32 v47, 16, v242
	v_cndmask_b32_e32 v46, v46, v48, vcc
	v_mul_f32_e32 v48, 0xbfb8aa3b, v47
	v_exp_f32_e32 v48, v48
	v_rsq_f32_e32 v46, v46
	v_add_f32_e32 v48, 1.0, v48
	v_rcp_f32_e32 v48, v48
	v_mul_f32_e32 v49, 0x45800000, v46
	v_cndmask_b32_e32 v46, v46, v49, vcc
	v_mul_f32_e32 v42, v42, v46
	v_mul_f32_e32 v42, v99, v42
	v_mul_f32_e32 v46, v48, v47
	v_mul_f32_e32 v42, v46, v42
	v_cvt_pk_bf16_f32 v42, v42, v195
	ds_read2st64_b32 v[120:121], v163 offset0:25 offset1:29
	ds_read_u16 v242, v62 offset:21384
	ds_read2st64_b32 v[126:127], v164 offset0:1 offset1:5
	ds_write_b16 v92, v42 offset:12544
	s_waitcnt lgkmcnt(8)
	v_add_f32_e32 v42, 0, v128
	v_add_f32_e32 v42, v42, v129
	ds_read2st64_b32 v[128:129], v164 offset0:9 offset1:13
	s_waitcnt lgkmcnt(9)
	v_add_f32_e32 v42, v42, v130
	v_add_f32_e32 v42, v42, v131
	s_waitcnt lgkmcnt(9)
	v_add_f32_e32 v42, v42, v118
	v_add_f32_e32 v42, v42, v119
	s_waitcnt lgkmcnt(1)
	v_add_f32_e32 v42, v42, v122
	ds_read2st64_b32 v[118:119], v164 offset0:17 offset1:21
	v_add_f32_e32 v42, v42, v123
	v_fmamk_f32 v42, v42, 0x3c000000, v1
	v_mul_f32_e32 v47, 0x4b800000, v42
	v_cmp_gt_f32_e32 vcc, s33, v42
	s_waitcnt lgkmcnt(2)
	v_lshlrev_b32_e32 v46, 16, v243
	v_cndmask_b32_e32 v42, v42, v47, vcc
	v_mul_f32_e32 v47, 0xbfb8aa3b, v46
	v_exp_f32_e32 v47, v47
	v_rsq_f32_e32 v42, v42
	v_add_f32_e32 v47, 1.0, v47
	v_rcp_f32_e32 v47, v47
	v_mul_f32_e32 v48, 0x45800000, v42
	v_cndmask_b32_e32 v42, v42, v48, vcc
	v_mul_f32_e32 v42, v43, v42
	v_mul_f32_e32 v42, v99, v42
	v_mul_f32_e32 v43, v47, v46
	v_mul_f32_e32 v42, v43, v42
	v_cvt_pk_bf16_f32 v46, v42, v195
	ds_read2st64_b32 v[122:123], v164 offset0:25 offset1:29
	ds_write_b16 v91, v46 offset:8192
	ds_read_u16 v243, v62 offset:21648
	ds_read2st64_b32 v[130:131], v165 offset0:1 offset1:5
	s_waitcnt lgkmcnt(6)
	v_add_f32_e32 v42, 0, v124
	v_add_f32_e32 v52, v42, v125
	ds_read2st64_b32 v[124:125], v165 offset0:9 offset1:13
	s_waitcnt lgkmcnt(3)
	v_add_f32_e32 v46, v52, v132
	v_add_f32_e32 v46, v46, v133
	s_waitcnt lgkmcnt(3)
	v_add_f32_e32 v46, v46, v116
	v_add_f32_e32 v46, v46, v117
	s_waitcnt lgkmcnt(3)
	v_add_f32_e32 v42, v46, v120
	v_add_f32_e32 v42, v42, v121
	ds_read2st64_b32 v[116:117], v165 offset0:17 offset1:21
	v_fmamk_f32 v42, v42, 0x3c000000, v1
	v_mul_f32_e32 v46, 0x4b800000, v42
	v_cmp_gt_f32_e32 vcc, s33, v42
	s_waitcnt lgkmcnt(4)
	v_lshlrev_b32_e32 v43, 16, v242
	v_cndmask_b32_e32 v42, v42, v46, vcc
	v_mul_f32_e32 v46, 0xbfb8aa3b, v43
	v_exp_f32_e32 v46, v46
	v_rsq_f32_e32 v42, v42
	v_add_f32_e32 v46, 1.0, v46
	v_rcp_f32_e32 v46, v46
	v_mul_f32_e32 v47, 0x45800000, v42
	v_cndmask_b32_e32 v42, v42, v47, vcc
	v_mul_f32_e32 v42, v44, v42
	v_mul_f32_e32 v42, v99, v42
	v_mul_f32_e32 v43, v46, v43
	v_mul_f32_e32 v42, v43, v42
	v_cvt_pk_bf16_f32 v44, v42, v195
	ds_read2st64_b32 v[120:121], v165 offset0:25 offset1:29
	ds_read_u16 v242, v62 offset:25080
	ds_read2st64_b32 v[132:133], v244 offset0:1 offset1:5
	ds_write_b16 v91, v44 offset:8464
	s_waitcnt lgkmcnt(8)
; #define LAS __attribute__((address_space(3)))
; __device__ __forceinline__ float bf2f(unsigned short b) { return __uint_as_float(((unsigned)b) << 16); }
; __device__ __forceinline__ unsigned short f2bf(float f) { return (unsigned short)(cvt_pk_bf16(f, 0.f) & 0xffffu); }
; __device__ void gla_C(const Params& P, int l, int item, LAS unsigned char* lds) {
;     ...
;     for (int rt = 0; rt < 16; ++rt)
; #pragma unroll
;         for (int jj = 0; jj < 4; ++jj) { const int t = rt * 16 + 4 * g + jj; float tot = 0.f;
; #pragma unroll
;             for (int ww = 0; ww < 8; ++ww) tot += SSQ[ww * 256 + t];
;             const float rs = rsqrtf(tot * (1.0f / 128.0f) + EPS);
;             const float gt = bf2f(*(const LAS unsigned short*)(GTL + t * 264 + (16 * w + c) * 2));
;             *(LAS unsigned short*)(OT + t * 272 + (16 * w + c) * 2) = f2bf(O[rt][jj] * rs * ng * (gt * __builtin_amdgcn_rcpf(1.0f + __expf(-gt)))); }
	v_add_f32_e32 v42, 0, v126
	v_add_f32_e32 v44, v42, v127
	ds_read2st64_b32 v[126:127], v244 offset0:9 offset1:13
	s_waitcnt lgkmcnt(9)
	v_add_f32_e32 v44, v44, v128
	v_add_f32_e32 v44, v44, v129
	s_waitcnt lgkmcnt(9)
	v_add_f32_e32 v44, v44, v118
	v_add_f32_e32 v44, v44, v119
	s_waitcnt lgkmcnt(1)
	v_add_f32_e32 v42, v44, v122
	v_add_f32_e32 v42, v42, v123
	ds_read2st64_b32 v[118:119], v244 offset0:17 offset1:21
	v_fmamk_f32 v42, v42, 0x3c000000, v1
	v_mul_f32_e32 v44, 0x4b800000, v42
	v_cmp_gt_f32_e32 vcc, s33, v42
	s_waitcnt lgkmcnt(2)
	v_lshlrev_b32_e32 v43, 16, v243
	v_cndmask_b32_e32 v42, v42, v44, vcc
	v_mul_f32_e32 v44, 0xbfb8aa3b, v43
	v_exp_f32_e32 v44, v44
	v_rsq_f32_e32 v42, v42
	v_add_f32_e32 v44, 1.0, v44
	v_rcp_f32_e32 v44, v44
	v_mul_f32_e32 v46, 0x45800000, v42
	v_cndmask_b32_e32 v42, v42, v46, vcc
	v_mul_f32_e32 v42, v45, v42
	v_mul_f32_e32 v42, v99, v42
	v_mul_f32_e32 v43, v44, v43
	v_mul_f32_e32 v42, v43, v42
	v_cvt_pk_bf16_f32 v44, v42, v195
	ds_read2st64_b32 v[122:123], v244 offset0:25 offset1:29
	ds_write_b16 v91, v44 offset:8736
	ds_read_u16 v243, v62 offset:25344
	ds_read2st64_b32 v[128:129], v245 offset0:1 offset1:5
	s_waitcnt lgkmcnt(6)
	v_add_f32_e32 v42, 0, v130
	v_add_f32_e32 v48, v42, v131
	ds_read2st64_b32 v[130:131], v245 offset0:9 offset1:13
	s_waitcnt lgkmcnt(3)
	v_add_f32_e32 v44, v48, v124
	v_add_f32_e32 v44, v44, v125
	s_waitcnt lgkmcnt(3)
	v_add_f32_e32 v44, v44, v116
	v_add_f32_e32 v44, v44, v117
	s_waitcnt lgkmcnt(3)
	v_add_f32_e32 v42, v44, v120
	v_add_f32_e32 v42, v42, v121
	ds_read2st64_b32 v[116:117], v245 offset0:17 offset1:21
	v_fmamk_f32 v42, v42, 0x3c000000, v1
	v_mul_f32_e32 v44, 0x4b800000, v42
	v_cmp_gt_f32_e32 vcc, s33, v42
	s_waitcnt lgkmcnt(4)
	v_lshlrev_b32_e32 v43, 16, v242
	v_cndmask_b32_e32 v42, v42, v44, vcc
	v_mul_f32_e32 v44, 0xbfb8aa3b, v43
	v_exp_f32_e32 v44, v44
	v_rsq_f32_e32 v42, v42
	v_add_f32_e32 v44, 1.0, v44
	v_rcp_f32_e32 v44, v44
	v_mul_f32_e32 v45, 0x45800000, v42
	v_cndmask_b32_e32 v42, v42, v45, vcc
	v_mul_f32_e32 v38, v38, v42
	v_mul_f32_e32 v38, v99, v38
	v_mul_f32_e32 v42, v44, v43
	v_mul_f32_e32 v38, v42, v38
	v_cvt_pk_bf16_f32 v38, v38, v195
	ds_read2st64_b32 v[120:121], v245 offset0:25 offset1:29
	ds_read_u16 v242, v62 offset:25608
	ds_read2st64_b32 v[124:125], v246 offset0:1 offset1:5
	ds_write_b16 v91, v38 offset:12272
	s_waitcnt lgkmcnt(8)
	v_add_f32_e32 v38, 0, v132
	v_add_f32_e32 v38, v38, v133
	ds_read2st64_b32 v[132:133], v246 offset0:9 offset1:13
	s_waitcnt lgkmcnt(9)
	v_add_f32_e32 v38, v38, v126
	v_add_f32_e32 v38, v38, v127
	s_waitcnt lgkmcnt(9)
	v_add_f32_e32 v38, v38, v118
	v_add_f32_e32 v38, v38, v119
	s_waitcnt lgkmcnt(1)
	v_add_f32_e32 v38, v38, v122
	ds_read2st64_b32 v[118:119], v246 offset0:17 offset1:21
	v_add_f32_e32 v38, v38, v123
	v_fmamk_f32 v38, v38, 0x3c000000, v1
	v_mul_f32_e32 v43, 0x4b800000, v38
	v_cmp_gt_f32_e32 vcc, s33, v38
	s_waitcnt lgkmcnt(2)
	v_lshlrev_b32_e32 v42, 16, v243
	v_cndmask_b32_e32 v38, v38, v43, vcc
	v_mul_f32_e32 v43, 0xbfb8aa3b, v42
	v_exp_f32_e32 v43, v43
	v_rsq_f32_e32 v38, v38
	v_add_f32_e32 v43, 1.0, v43
	v_rcp_f32_e32 v43, v43
	v_mul_f32_e32 v44, 0x45800000, v38
	v_cndmask_b32_e32 v38, v38, v44, vcc
	v_mul_f32_e32 v38, v39, v38
	v_mul_f32_e32 v38, v99, v38
	v_mul_f32_e32 v39, v43, v42
	v_mul_f32_e32 v38, v39, v38
	v_cvt_pk_bf16_f32 v42, v38, v195
	ds_read2st64_b32 v[122:123], v246 offset0:25 offset1:29
	ds_write_b16 v91, v42 offset:12544
	ds_read_u16 v243, v62 offset:25872
	ds_read2st64_b32 v[126:127], v247 offset0:1 offset1:5
	s_waitcnt lgkmcnt(6)
	v_add_f32_e32 v38, 0, v128
	v_add_f32_e32 v46, v38, v129
	ds_read2st64_b32 v[128:129], v247 offset0:9 offset1:13
	s_waitcnt lgkmcnt(3)
	v_add_f32_e32 v42, v46, v130
	v_add_f32_e32 v42, v42, v131
	s_waitcnt lgkmcnt(3)
	v_add_f32_e32 v42, v42, v116
	v_add_f32_e32 v42, v42, v117
	s_waitcnt lgkmcnt(3)
	v_add_f32_e32 v38, v42, v120
	v_add_f32_e32 v38, v38, v121
	ds_read2st64_b32 v[116:117], v247 offset0:17 offset1:21
	v_fmamk_f32 v38, v38, 0x3c000000, v1
	v_mul_f32_e32 v42, 0x4b800000, v38
	v_cmp_gt_f32_e32 vcc, s33, v38
	s_waitcnt lgkmcnt(4)
	v_lshlrev_b32_e32 v39, 16, v242
	v_cndmask_b32_e32 v38, v38, v42, vcc
	v_mul_f32_e32 v42, 0xbfb8aa3b, v39
	v_exp_f32_e32 v42, v42
	v_rsq_f32_e32 v38, v38
	v_add_f32_e32 v42, 1.0, v42
	v_rcp_f32_e32 v42, v42
	v_mul_f32_e32 v43, 0x45800000, v38
	v_cndmask_b32_e32 v38, v38, v43, vcc
	v_mul_f32_e32 v38, v40, v38
	v_mul_f32_e32 v38, v99, v38
	v_mul_f32_e32 v39, v42, v39
	v_mul_f32_e32 v38, v39, v38
	v_cvt_pk_bf16_f32 v40, v38, v195
	ds_read2st64_b32 v[120:121], v247 offset0:25 offset1:29
	ds_read_u16 v242, v62 offset:29304
	ds_read2st64_b32 v[130:131], v248 offset0:1 offset1:5
	ds_write_b16 v90, v40 offset:8192
	s_waitcnt lgkmcnt(8)
	v_add_f32_e32 v38, 0, v124
	v_add_f32_e32 v40, v38, v125
	ds_read2st64_b32 v[124:125], v248 offset0:9 offset1:13
	s_waitcnt lgkmcnt(9)
	v_add_f32_e32 v40, v40, v132
	v_add_f32_e32 v40, v40, v133
	s_waitcnt lgkmcnt(9)
	v_add_f32_e32 v40, v40, v118
	v_add_f32_e32 v40, v40, v119
	s_waitcnt lgkmcnt(1)
	v_add_f32_e32 v38, v40, v122
	v_add_f32_e32 v38, v38, v123
	ds_read2st64_b32 v[118:119], v248 offset0:17 offset1:21
	v_fmamk_f32 v38, v38, 0x3c000000, v1
	v_mul_f32_e32 v40, 0x4b800000, v38
	v_cmp_gt_f32_e32 vcc, s33, v38
	s_waitcnt lgkmcnt(2)
	v_lshlrev_b32_e32 v39, 16, v243
	v_cndmask_b32_e32 v38, v38, v40, vcc
	v_mul_f32_e32 v40, 0xbfb8aa3b, v39
	v_exp_f32_e32 v40, v40
	v_rsq_f32_e32 v38, v38
	v_add_f32_e32 v40, 1.0, v40
	v_rcp_f32_e32 v40, v40
	v_mul_f32_e32 v42, 0x45800000, v38
	v_cndmask_b32_e32 v38, v38, v42, vcc
	v_mul_f32_e32 v38, v41, v38
	v_mul_f32_e32 v38, v99, v38
	v_mul_f32_e32 v39, v40, v39
	v_mul_f32_e32 v38, v39, v38
	v_cvt_pk_bf16_f32 v40, v38, v195
	ds_read2st64_b32 v[122:123], v248 offset0:25 offset1:29
	ds_write_b16 v90, v40 offset:8464
	ds_read_u16 v243, v62 offset:29568
	ds_read2st64_b32 v[132:133], v249 offset0:1 offset1:5
	s_waitcnt lgkmcnt(6)
; #define LAS __attribute__((address_space(3)))
; __device__ __forceinline__ float bf2f(unsigned short b) { return __uint_as_float(((unsigned)b) << 16); }
; __device__ __forceinline__ unsigned short f2bf(float f) { return (unsigned short)(cvt_pk_bf16(f, 0.f) & 0xffffu); }
; __device__ void gla_C(const Params& P, int l, int item, LAS unsigned char* lds) {
;     ...
;     for (int rt = 0; rt < 16; ++rt)
; #pragma unroll
;         for (int jj = 0; jj < 4; ++jj) { const int t = rt * 16 + 4 * g + jj; float tot = 0.f;
; #pragma unroll
;             for (int ww = 0; ww < 8; ++ww) tot += SSQ[ww * 256 + t];
;             const float rs = rsqrtf(tot * (1.0f / 128.0f) + EPS);
;             const float gt = bf2f(*(const LAS unsigned short*)(GTL + t * 264 + (16 * w + c) * 2));
;             *(LAS unsigned short*)(OT + t * 272 + (16 * w + c) * 2) = f2bf(O[rt][jj] * rs * ng * (gt * __builtin_amdgcn_rcpf(1.0f + __expf(-gt)))); }
	v_add_f32_e32 v38, 0, v126
	v_add_f32_e32 v44, v38, v127
	ds_read2st64_b32 v[126:127], v249 offset0:9 offset1:13
	s_waitcnt lgkmcnt(3)
	v_add_f32_e32 v40, v44, v128
	v_add_f32_e32 v40, v40, v129
	s_waitcnt lgkmcnt(3)
	v_add_f32_e32 v40, v40, v116
	v_add_f32_e32 v40, v40, v117
	s_waitcnt lgkmcnt(3)
	v_add_f32_e32 v38, v40, v120
	v_add_f32_e32 v38, v38, v121
	ds_read2st64_b32 v[116:117], v249 offset0:17 offset1:21
	v_fmamk_f32 v38, v38, 0x3c000000, v1
	v_mul_f32_e32 v40, 0x4b800000, v38
	v_cmp_gt_f32_e32 vcc, s33, v38
	s_waitcnt lgkmcnt(4)
	v_lshlrev_b32_e32 v39, 16, v242
	v_cndmask_b32_e32 v38, v38, v40, vcc
	v_mul_f32_e32 v40, 0xbfb8aa3b, v39
	v_exp_f32_e32 v40, v40
	v_rsq_f32_e32 v38, v38
	v_add_f32_e32 v40, 1.0, v40
	v_rcp_f32_e32 v40, v40
	v_mul_f32_e32 v41, 0x45800000, v38
	v_cndmask_b32_e32 v38, v38, v41, vcc
	v_mul_f32_e32 v34, v34, v38
	v_mul_f32_e32 v34, v99, v34
	v_mul_f32_e32 v38, v40, v39
	v_mul_f32_e32 v34, v38, v34
	v_cvt_pk_bf16_f32 v34, v34, v195
	ds_read2st64_b32 v[120:121], v249 offset0:25 offset1:29
	ds_read_u16 v242, v62 offset:29832
	ds_read2st64_b32 v[128:129], v236 offset0:1 offset1:5
	ds_write_b16 v90, v34 offset:12000
	s_waitcnt lgkmcnt(8)
	v_add_f32_e32 v34, 0, v130
	v_add_f32_e32 v34, v34, v131
	ds_read2st64_b32 v[130:131], v236 offset0:9 offset1:13
	s_waitcnt lgkmcnt(9)
	v_add_f32_e32 v34, v34, v124
	v_add_f32_e32 v34, v34, v125
	s_waitcnt lgkmcnt(9)
	v_add_f32_e32 v34, v34, v118
	v_add_f32_e32 v34, v34, v119
	s_waitcnt lgkmcnt(1)
	v_add_f32_e32 v34, v34, v122
	ds_read2st64_b32 v[118:119], v236 offset0:17 offset1:21
	v_add_f32_e32 v34, v34, v123
	v_fmamk_f32 v34, v34, 0x3c000000, v1
	v_mul_f32_e32 v39, 0x4b800000, v34
	v_cmp_gt_f32_e32 vcc, s33, v34
	s_waitcnt lgkmcnt(2)
	v_lshlrev_b32_e32 v38, 16, v243
	v_cndmask_b32_e32 v34, v34, v39, vcc
	v_mul_f32_e32 v39, 0xbfb8aa3b, v38
	v_exp_f32_e32 v39, v39
	v_rsq_f32_e32 v34, v34
	v_add_f32_e32 v39, 1.0, v39
	v_rcp_f32_e32 v39, v39
	v_mul_f32_e32 v40, 0x45800000, v34
	v_cndmask_b32_e32 v34, v34, v40, vcc
	v_mul_f32_e32 v34, v35, v34
	v_mul_f32_e32 v34, v99, v34
	v_mul_f32_e32 v35, v39, v38
	v_mul_f32_e32 v34, v35, v34
	v_cvt_pk_bf16_f32 v38, v34, v195
	ds_read2st64_b32 v[122:123], v236 offset0:25 offset1:29
	ds_write_b16 v90, v38 offset:12272
	ds_read_u16 v243, v62 offset:30096
	ds_read2st64_b32 v[124:125], v66 offset0:2 offset1:6
	s_waitcnt lgkmcnt(6)
	v_add_f32_e32 v34, 0, v132
	v_add_f32_e32 v42, v34, v133
	ds_read2st64_b32 v[132:133], v66 offset0:10 offset1:14
	s_waitcnt lgkmcnt(3)
	v_add_f32_e32 v38, v42, v126
	v_add_f32_e32 v38, v38, v127
	s_waitcnt lgkmcnt(3)
	v_add_f32_e32 v38, v38, v116
	v_add_f32_e32 v38, v38, v117
	s_waitcnt lgkmcnt(3)
	v_add_f32_e32 v34, v38, v120
	v_add_f32_e32 v34, v34, v121
	ds_read2st64_b32 v[116:117], v66 offset0:18 offset1:22
	v_fmamk_f32 v34, v34, 0x3c000000, v1
	v_mul_f32_e32 v38, 0x4b800000, v34
	v_cmp_gt_f32_e32 vcc, s33, v34
	s_waitcnt lgkmcnt(4)
	v_lshlrev_b32_e32 v35, 16, v242
	v_cndmask_b32_e32 v34, v34, v38, vcc
	v_mul_f32_e32 v38, 0xbfb8aa3b, v35
	v_exp_f32_e32 v38, v38
	v_rsq_f32_e32 v34, v34
	v_add_f32_e32 v38, 1.0, v38
	v_rcp_f32_e32 v38, v38
	v_mul_f32_e32 v39, 0x45800000, v34
	v_cndmask_b32_e32 v34, v34, v39, vcc
	v_mul_f32_e32 v34, v36, v34
	v_mul_f32_e32 v34, v99, v34
	v_mul_f32_e32 v35, v38, v35
	v_mul_f32_e32 v34, v35, v34
	v_cvt_pk_bf16_f32 v36, v34, v195
	ds_read2st64_b32 v[120:121], v66 offset0:26 offset1:30
	ds_read_u16 v242, v62 offset:33528
	ds_read2st64_b32 v[126:127], v158 offset0:2 offset1:6
	ds_write_b16 v90, v36 offset:12544
	s_waitcnt lgkmcnt(8)
	v_add_f32_e32 v34, 0, v128
	v_add_f32_e32 v36, v34, v129
	ds_read2st64_b32 v[128:129], v158 offset0:10 offset1:14
	s_waitcnt lgkmcnt(9)
	v_add_f32_e32 v36, v36, v130
	v_add_f32_e32 v36, v36, v131
	s_waitcnt lgkmcnt(9)
	v_add_f32_e32 v36, v36, v118
	v_add_f32_e32 v36, v36, v119
	s_waitcnt lgkmcnt(1)
	v_add_f32_e32 v34, v36, v122
	v_add_f32_e32 v34, v34, v123
	ds_read2st64_b32 v[118:119], v158 offset0:18 offset1:22
	v_fmamk_f32 v34, v34, 0x3c000000, v1
	v_mul_f32_e32 v36, 0x4b800000, v34
	v_cmp_gt_f32_e32 vcc, s33, v34
	s_waitcnt lgkmcnt(2)
	v_lshlrev_b32_e32 v35, 16, v243
	v_cndmask_b32_e32 v34, v34, v36, vcc
	v_mul_f32_e32 v36, 0xbfb8aa3b, v35
	v_exp_f32_e32 v36, v36
	v_rsq_f32_e32 v34, v34
	v_add_f32_e32 v36, 1.0, v36
	v_rcp_f32_e32 v36, v36
	v_mul_f32_e32 v38, 0x45800000, v34
	v_cndmask_b32_e32 v34, v34, v38, vcc
	v_mul_f32_e32 v34, v37, v34
	v_mul_f32_e32 v34, v99, v34
	v_mul_f32_e32 v35, v36, v35
	v_mul_f32_e32 v34, v35, v34
	v_cvt_pk_bf16_f32 v36, v34, v195
	ds_read2st64_b32 v[122:123], v158 offset0:26 offset1:30
	ds_write_b16 v89, v36 offset:8192
	ds_read_u16 v243, v62 offset:33792
	ds_read2st64_b32 v[130:131], v159 offset0:2 offset1:6
	s_waitcnt lgkmcnt(6)
	v_add_f32_e32 v34, 0, v124
	v_add_f32_e32 v40, v34, v125
	ds_read2st64_b32 v[124:125], v159 offset0:10 offset1:14
	s_waitcnt lgkmcnt(3)
	v_add_f32_e32 v36, v40, v132
	v_add_f32_e32 v36, v36, v133
	s_waitcnt lgkmcnt(3)
	v_add_f32_e32 v36, v36, v116
	v_add_f32_e32 v36, v36, v117
	s_waitcnt lgkmcnt(3)
	v_add_f32_e32 v34, v36, v120
	v_add_f32_e32 v34, v34, v121
	ds_read2st64_b32 v[116:117], v159 offset0:18 offset1:22
	v_fmamk_f32 v34, v34, 0x3c000000, v1
	v_mul_f32_e32 v36, 0x4b800000, v34
	v_cmp_gt_f32_e32 vcc, s33, v34
	s_waitcnt lgkmcnt(4)
	v_lshlrev_b32_e32 v35, 16, v242
	v_cndmask_b32_e32 v34, v34, v36, vcc
	v_mul_f32_e32 v36, 0xbfb8aa3b, v35
	v_exp_f32_e32 v36, v36
	v_rsq_f32_e32 v34, v34
	v_add_f32_e32 v36, 1.0, v36
	v_rcp_f32_e32 v36, v36
	v_mul_f32_e32 v37, 0x45800000, v34
	v_cndmask_b32_e32 v34, v34, v37, vcc
	v_mul_f32_e32 v30, v30, v34
	v_mul_f32_e32 v30, v99, v30
	v_mul_f32_e32 v34, v36, v35
	v_mul_f32_e32 v30, v34, v30
	v_cvt_pk_bf16_f32 v30, v30, v195
	ds_read2st64_b32 v[120:121], v159 offset0:26 offset1:30
	ds_read_u16 v242, v62 offset:34056
	ds_read2st64_b32 v[132:133], v160 offset0:2 offset1:6
	ds_write_b16 v89, v30 offset:11728
	s_waitcnt lgkmcnt(8)
; #define LAS __attribute__((address_space(3)))
; __device__ __forceinline__ float bf2f(unsigned short b) { return __uint_as_float(((unsigned)b) << 16); }
; __device__ __forceinline__ unsigned short f2bf(float f) { return (unsigned short)(cvt_pk_bf16(f, 0.f) & 0xffffu); }
; __device__ void gla_C(const Params& P, int l, int item, LAS unsigned char* lds) {
;     ...
;     for (int rt = 0; rt < 16; ++rt)
; #pragma unroll
;         for (int jj = 0; jj < 4; ++jj) { const int t = rt * 16 + 4 * g + jj; float tot = 0.f;
; #pragma unroll
;             for (int ww = 0; ww < 8; ++ww) tot += SSQ[ww * 256 + t];
;             const float rs = rsqrtf(tot * (1.0f / 128.0f) + EPS);
;             const float gt = bf2f(*(const LAS unsigned short*)(GTL + t * 264 + (16 * w + c) * 2));
;             *(LAS unsigned short*)(OT + t * 272 + (16 * w + c) * 2) = f2bf(O[rt][jj] * rs * ng * (gt * __builtin_amdgcn_rcpf(1.0f + __expf(-gt)))); }
	v_add_f32_e32 v30, 0, v126
	v_add_f32_e32 v30, v30, v127
	ds_read2st64_b32 v[126:127], v160 offset0:10 offset1:14
	s_waitcnt lgkmcnt(9)
	v_add_f32_e32 v30, v30, v128
	v_add_f32_e32 v30, v30, v129
	s_waitcnt lgkmcnt(9)
	v_add_f32_e32 v30, v30, v118
	v_add_f32_e32 v30, v30, v119
	s_waitcnt lgkmcnt(1)
	v_add_f32_e32 v30, v30, v122
	ds_read2st64_b32 v[118:119], v160 offset0:18 offset1:22
	v_add_f32_e32 v30, v30, v123
	v_fmamk_f32 v30, v30, 0x3c000000, v1
	v_mul_f32_e32 v35, 0x4b800000, v30
	v_cmp_gt_f32_e32 vcc, s33, v30
	s_waitcnt lgkmcnt(2)
	v_lshlrev_b32_e32 v34, 16, v243
	v_cndmask_b32_e32 v30, v30, v35, vcc
	v_mul_f32_e32 v35, 0xbfb8aa3b, v34
	v_exp_f32_e32 v35, v35
	v_rsq_f32_e32 v30, v30
	v_add_f32_e32 v35, 1.0, v35
	v_rcp_f32_e32 v35, v35
	v_mul_f32_e32 v36, 0x45800000, v30
	v_cndmask_b32_e32 v30, v30, v36, vcc
	v_mul_f32_e32 v30, v31, v30
	v_mul_f32_e32 v30, v99, v30
	v_mul_f32_e32 v31, v35, v34
	v_mul_f32_e32 v30, v31, v30
	v_cvt_pk_bf16_f32 v34, v30, v195
	ds_read2st64_b32 v[122:123], v160 offset0:26 offset1:30
	ds_write_b16 v89, v34 offset:12000
	ds_read_u16 v243, v62 offset:34320
	ds_read2st64_b32 v[128:129], v161 offset0:2 offset1:6
	s_waitcnt lgkmcnt(6)
	v_add_f32_e32 v30, 0, v130
	v_add_f32_e32 v38, v30, v131
	ds_read2st64_b32 v[130:131], v161 offset0:10 offset1:14
	s_waitcnt lgkmcnt(3)
	v_add_f32_e32 v34, v38, v124
	v_add_f32_e32 v34, v34, v125
	s_waitcnt lgkmcnt(3)
	v_add_f32_e32 v34, v34, v116
	v_add_f32_e32 v34, v34, v117
	s_waitcnt lgkmcnt(3)
	v_add_f32_e32 v30, v34, v120
	v_add_f32_e32 v30, v30, v121
	ds_read2st64_b32 v[116:117], v161 offset0:18 offset1:22
	v_fmamk_f32 v30, v30, 0x3c000000, v1
	v_mul_f32_e32 v34, 0x4b800000, v30
	v_cmp_gt_f32_e32 vcc, s33, v30
	s_waitcnt lgkmcnt(4)
	v_lshlrev_b32_e32 v31, 16, v242
	v_cndmask_b32_e32 v30, v30, v34, vcc
	v_mul_f32_e32 v34, 0xbfb8aa3b, v31
	v_exp_f32_e32 v34, v34
	v_rsq_f32_e32 v30, v30
	v_add_f32_e32 v34, 1.0, v34
	v_rcp_f32_e32 v34, v34
	v_mul_f32_e32 v35, 0x45800000, v30
	v_cndmask_b32_e32 v30, v30, v35, vcc
	v_mul_f32_e32 v30, v32, v30
	v_mul_f32_e32 v30, v99, v30
	v_mul_f32_e32 v31, v34, v31
	v_mul_f32_e32 v30, v31, v30
	v_cvt_pk_bf16_f32 v32, v30, v195
	ds_read2st64_b32 v[120:121], v161 offset0:26 offset1:30
	ds_read_u16 v242, v62 offset:37752
	ds_read2st64_b32 v[124:125], v162 offset0:2 offset1:6
	ds_write_b16 v89, v32 offset:12272
	s_waitcnt lgkmcnt(8)
	v_add_f32_e32 v30, 0, v132
	v_add_f32_e32 v32, v30, v133
	ds_read2st64_b32 v[132:133], v162 offset0:10 offset1:14
	s_waitcnt lgkmcnt(9)
	v_add_f32_e32 v32, v32, v126
	v_add_f32_e32 v32, v32, v127
	s_waitcnt lgkmcnt(9)
	v_add_f32_e32 v32, v32, v118
	v_add_f32_e32 v32, v32, v119
	s_waitcnt lgkmcnt(1)
	v_add_f32_e32 v30, v32, v122
	v_add_f32_e32 v30, v30, v123
	ds_read2st64_b32 v[118:119], v162 offset0:18 offset1:22
	v_fmamk_f32 v30, v30, 0x3c000000, v1
	v_mul_f32_e32 v32, 0x4b800000, v30
	v_cmp_gt_f32_e32 vcc, s33, v30
	s_waitcnt lgkmcnt(2)
	v_lshlrev_b32_e32 v31, 16, v243
	v_cndmask_b32_e32 v30, v30, v32, vcc
	v_mul_f32_e32 v32, 0xbfb8aa3b, v31
	v_exp_f32_e32 v32, v32
	v_rsq_f32_e32 v30, v30
	v_add_f32_e32 v32, 1.0, v32
	v_rcp_f32_e32 v32, v32
	v_mul_f32_e32 v34, 0x45800000, v30
	v_cndmask_b32_e32 v30, v30, v34, vcc
	v_mul_f32_e32 v30, v33, v30
	v_mul_f32_e32 v30, v99, v30
	v_mul_f32_e32 v31, v32, v31
	v_mul_f32_e32 v30, v31, v30
	v_cvt_pk_bf16_f32 v32, v30, v195
	ds_read2st64_b32 v[122:123], v162 offset0:26 offset1:30
	ds_write_b16 v89, v32 offset:12544
	ds_read_u16 v243, v62 offset:38016
	ds_read2st64_b32 v[126:127], v163 offset0:2 offset1:6
	s_waitcnt lgkmcnt(6)
	v_add_f32_e32 v30, 0, v128
	v_add_f32_e32 v36, v30, v129
	ds_read2st64_b32 v[128:129], v163 offset0:10 offset1:14
	s_waitcnt lgkmcnt(3)
	v_add_f32_e32 v32, v36, v130
	v_add_f32_e32 v32, v32, v131
	s_waitcnt lgkmcnt(3)
	v_add_f32_e32 v32, v32, v116
	v_add_f32_e32 v32, v32, v117
	s_waitcnt lgkmcnt(3)
	v_add_f32_e32 v30, v32, v120
	v_add_f32_e32 v30, v30, v121
	ds_read2st64_b32 v[116:117], v163 offset0:18 offset1:22
	v_fmamk_f32 v30, v30, 0x3c000000, v1
	v_mul_f32_e32 v32, 0x4b800000, v30
	v_cmp_gt_f32_e32 vcc, s33, v30
	s_waitcnt lgkmcnt(4)
	v_lshlrev_b32_e32 v31, 16, v242
	v_cndmask_b32_e32 v30, v30, v32, vcc
	v_mul_f32_e32 v32, 0xbfb8aa3b, v31
	v_exp_f32_e32 v32, v32
	v_rsq_f32_e32 v30, v30
	v_add_f32_e32 v32, 1.0, v32
	v_rcp_f32_e32 v32, v32
	v_mul_f32_e32 v33, 0x45800000, v30
	v_cndmask_b32_e32 v30, v30, v33, vcc
	v_mul_f32_e32 v26, v26, v30
	v_mul_f32_e32 v26, v99, v26
	v_mul_f32_e32 v30, v32, v31
	v_mul_f32_e32 v26, v30, v26
	v_cvt_pk_bf16_f32 v26, v26, v195
	ds_read2st64_b32 v[120:121], v163 offset0:26 offset1:30
	ds_read_u16 v242, v62 offset:38280
	ds_read2st64_b32 v[130:131], v164 offset0:2 offset1:6
	ds_write_b16 v88, v26 offset:8192
	s_waitcnt lgkmcnt(8)
	v_add_f32_e32 v26, 0, v124
	v_add_f32_e32 v26, v26, v125
	ds_read2st64_b32 v[124:125], v164 offset0:10 offset1:14
	s_waitcnt lgkmcnt(9)
	v_add_f32_e32 v26, v26, v132
	v_add_f32_e32 v26, v26, v133
	s_waitcnt lgkmcnt(9)
	v_add_f32_e32 v26, v26, v118
	v_add_f32_e32 v26, v26, v119
	s_waitcnt lgkmcnt(1)
	v_add_f32_e32 v26, v26, v122
	ds_read2st64_b32 v[118:119], v164 offset0:18 offset1:22
	v_add_f32_e32 v26, v26, v123
	v_fmamk_f32 v26, v26, 0x3c000000, v1
	v_mul_f32_e32 v31, 0x4b800000, v26
	v_cmp_gt_f32_e32 vcc, s33, v26
	s_waitcnt lgkmcnt(2)
	v_lshlrev_b32_e32 v30, 16, v243
	v_cndmask_b32_e32 v26, v26, v31, vcc
	v_mul_f32_e32 v31, 0xbfb8aa3b, v30
	v_exp_f32_e32 v31, v31
	v_rsq_f32_e32 v26, v26
	v_add_f32_e32 v31, 1.0, v31
	v_rcp_f32_e32 v31, v31
	v_mul_f32_e32 v32, 0x45800000, v26
	v_cndmask_b32_e32 v26, v26, v32, vcc
	v_mul_f32_e32 v26, v27, v26
	v_mul_f32_e32 v26, v99, v26
	v_mul_f32_e32 v27, v31, v30
	v_mul_f32_e32 v26, v27, v26
	v_cvt_pk_bf16_f32 v30, v26, v195
	ds_read2st64_b32 v[122:123], v164 offset0:26 offset1:30
	ds_write_b16 v88, v30 offset:8464
	ds_read_u16 v243, v62 offset:38544
	ds_read2st64_b32 v[132:133], v165 offset0:2 offset1:6
	s_waitcnt lgkmcnt(6)
; #define LAS __attribute__((address_space(3)))
; __device__ __forceinline__ float bf2f(unsigned short b) { return __uint_as_float(((unsigned)b) << 16); }
; __device__ __forceinline__ unsigned short f2bf(float f) { return (unsigned short)(cvt_pk_bf16(f, 0.f) & 0xffffu); }
; __device__ void gla_C(const Params& P, int l, int item, LAS unsigned char* lds) {
;     ...
;     for (int rt = 0; rt < 16; ++rt)
; #pragma unroll
;         for (int jj = 0; jj < 4; ++jj) { const int t = rt * 16 + 4 * g + jj; float tot = 0.f;
; #pragma unroll
;             for (int ww = 0; ww < 8; ++ww) tot += SSQ[ww * 256 + t];
;             const float rs = rsqrtf(tot * (1.0f / 128.0f) + EPS);
;             const float gt = bf2f(*(const LAS unsigned short*)(GTL + t * 264 + (16 * w + c) * 2));
;             *(LAS unsigned short*)(OT + t * 272 + (16 * w + c) * 2) = f2bf(O[rt][jj] * rs * ng * (gt * __builtin_amdgcn_rcpf(1.0f + __expf(-gt)))); }
	v_add_f32_e32 v26, 0, v126
	v_add_f32_e32 v34, v26, v127
	ds_read2st64_b32 v[126:127], v165 offset0:10 offset1:14
	s_waitcnt lgkmcnt(3)
	v_add_f32_e32 v30, v34, v128
	v_add_f32_e32 v30, v30, v129
	s_waitcnt lgkmcnt(3)
	v_add_f32_e32 v30, v30, v116
	v_add_f32_e32 v30, v30, v117
	s_waitcnt lgkmcnt(3)
	v_add_f32_e32 v26, v30, v120
	v_add_f32_e32 v26, v26, v121
	ds_read2st64_b32 v[116:117], v165 offset0:18 offset1:22
	v_fmamk_f32 v26, v26, 0x3c000000, v1
	v_mul_f32_e32 v30, 0x4b800000, v26
	v_cmp_gt_f32_e32 vcc, s33, v26
	s_waitcnt lgkmcnt(4)
	v_lshlrev_b32_e32 v27, 16, v242
	v_cndmask_b32_e32 v26, v26, v30, vcc
	v_mul_f32_e32 v30, 0xbfb8aa3b, v27
	v_exp_f32_e32 v30, v30
	v_rsq_f32_e32 v26, v26
	v_add_f32_e32 v30, 1.0, v30
	v_rcp_f32_e32 v30, v30
	v_mul_f32_e32 v31, 0x45800000, v26
	v_cndmask_b32_e32 v26, v26, v31, vcc
	v_mul_f32_e32 v26, v28, v26
	v_mul_f32_e32 v26, v99, v26
	v_mul_f32_e32 v27, v30, v27
	v_mul_f32_e32 v26, v27, v26
	v_cvt_pk_bf16_f32 v28, v26, v195
	ds_read2st64_b32 v[120:121], v165 offset0:26 offset1:30
	ds_read_u16 v242, v62 offset:41976
	ds_read2st64_b32 v[128:129], v244 offset0:2 offset1:6
	ds_write_b16 v88, v28 offset:8736
	s_waitcnt lgkmcnt(8)
	v_add_f32_e32 v26, 0, v130
	v_add_f32_e32 v28, v26, v131
	ds_read2st64_b32 v[130:131], v244 offset0:10 offset1:14
	s_waitcnt lgkmcnt(9)
	v_add_f32_e32 v28, v28, v124
	v_add_f32_e32 v28, v28, v125
	s_waitcnt lgkmcnt(9)
	v_add_f32_e32 v28, v28, v118
	v_add_f32_e32 v28, v28, v119
	s_waitcnt lgkmcnt(1)
	v_add_f32_e32 v26, v28, v122
	v_add_f32_e32 v26, v26, v123
	ds_read2st64_b32 v[118:119], v244 offset0:18 offset1:22
	v_fmamk_f32 v26, v26, 0x3c000000, v1
	v_mul_f32_e32 v28, 0x4b800000, v26
	v_cmp_gt_f32_e32 vcc, s33, v26
	s_waitcnt lgkmcnt(2)
	v_lshlrev_b32_e32 v27, 16, v243
	v_cndmask_b32_e32 v26, v26, v28, vcc
	v_mul_f32_e32 v28, 0xbfb8aa3b, v27
	v_exp_f32_e32 v28, v28
	v_rsq_f32_e32 v26, v26
	v_add_f32_e32 v28, 1.0, v28
	v_rcp_f32_e32 v28, v28
	v_mul_f32_e32 v30, 0x45800000, v26
	v_cndmask_b32_e32 v26, v26, v30, vcc
	v_mul_f32_e32 v26, v29, v26
	v_mul_f32_e32 v26, v99, v26
	v_mul_f32_e32 v27, v28, v27
	v_mul_f32_e32 v26, v27, v26
	v_cvt_pk_bf16_f32 v28, v26, v195
	ds_read2st64_b32 v[122:123], v244 offset0:26 offset1:30
	ds_write_b16 v88, v28 offset:9008
	ds_read_u16 v243, v62 offset:42240
	ds_read2st64_b32 v[124:125], v245 offset0:2 offset1:6
	s_waitcnt lgkmcnt(6)
	v_add_f32_e32 v26, 0, v132
	v_add_f32_e32 v32, v26, v133
	ds_read2st64_b32 v[132:133], v245 offset0:10 offset1:14
	s_waitcnt lgkmcnt(3)
	v_add_f32_e32 v28, v32, v126
	v_add_f32_e32 v28, v28, v127
	s_waitcnt lgkmcnt(3)
	v_add_f32_e32 v28, v28, v116
	v_add_f32_e32 v28, v28, v117
	s_waitcnt lgkmcnt(3)
	v_add_f32_e32 v26, v28, v120
	v_add_f32_e32 v26, v26, v121
	ds_read2st64_b32 v[116:117], v245 offset0:18 offset1:22
	v_fmamk_f32 v26, v26, 0x3c000000, v1
	v_mul_f32_e32 v28, 0x4b800000, v26
	v_cmp_gt_f32_e32 vcc, s33, v26
	s_waitcnt lgkmcnt(4)
	v_lshlrev_b32_e32 v27, 16, v242
	v_cndmask_b32_e32 v26, v26, v28, vcc
	v_mul_f32_e32 v28, 0xbfb8aa3b, v27
	v_exp_f32_e32 v28, v28
	v_rsq_f32_e32 v26, v26
	v_add_f32_e32 v28, 1.0, v28
	v_rcp_f32_e32 v28, v28
	v_mul_f32_e32 v29, 0x45800000, v26
	v_cndmask_b32_e32 v26, v26, v29, vcc
	v_mul_f32_e32 v22, v22, v26
	v_mul_f32_e32 v22, v99, v22
	v_mul_f32_e32 v26, v28, v27
	v_mul_f32_e32 v22, v26, v22
	v_cvt_pk_bf16_f32 v22, v22, v195
	ds_read2st64_b32 v[120:121], v245 offset0:26 offset1:30
	ds_read_u16 v242, v62 offset:42504
	ds_read2st64_b32 v[126:127], v246 offset0:2 offset1:6
	ds_write_b16 v88, v22 offset:12544
	s_waitcnt lgkmcnt(8)
	v_add_f32_e32 v22, 0, v128
	v_add_f32_e32 v22, v22, v129
	ds_read2st64_b32 v[128:129], v246 offset0:10 offset1:14
	s_waitcnt lgkmcnt(9)
	v_add_f32_e32 v22, v22, v130
	v_add_f32_e32 v22, v22, v131
	s_waitcnt lgkmcnt(9)
	v_add_f32_e32 v22, v22, v118
	v_add_f32_e32 v22, v22, v119
	s_waitcnt lgkmcnt(1)
	v_add_f32_e32 v22, v22, v122
	ds_read2st64_b32 v[118:119], v246 offset0:18 offset1:22
	v_add_f32_e32 v22, v22, v123
	v_fmamk_f32 v22, v22, 0x3c000000, v1
	v_mul_f32_e32 v27, 0x4b800000, v22
	v_cmp_gt_f32_e32 vcc, s33, v22
	s_waitcnt lgkmcnt(2)
	v_lshlrev_b32_e32 v26, 16, v243
	v_cndmask_b32_e32 v22, v22, v27, vcc
	v_mul_f32_e32 v27, 0xbfb8aa3b, v26
	v_exp_f32_e32 v27, v27
	v_rsq_f32_e32 v22, v22
	v_add_f32_e32 v27, 1.0, v27
	v_rcp_f32_e32 v27, v27
	v_mul_f32_e32 v28, 0x45800000, v22
	v_cndmask_b32_e32 v22, v22, v28, vcc
	v_mul_f32_e32 v22, v23, v22
	v_mul_f32_e32 v22, v99, v22
	v_mul_f32_e32 v23, v27, v26
	v_mul_f32_e32 v22, v23, v22
	v_cvt_pk_bf16_f32 v26, v22, v195
	ds_read2st64_b32 v[122:123], v246 offset0:26 offset1:30
	ds_write_b16 v87, v26 offset:8192
	ds_read_u16 v243, v62 offset:42768
	ds_read2st64_b32 v[130:131], v247 offset0:2 offset1:6
	s_waitcnt lgkmcnt(6)
	v_add_f32_e32 v22, 0, v124
	v_add_f32_e32 v30, v22, v125
	ds_read2st64_b32 v[124:125], v247 offset0:10 offset1:14
	s_waitcnt lgkmcnt(3)
	v_add_f32_e32 v26, v30, v132
	v_add_f32_e32 v26, v26, v133
	s_waitcnt lgkmcnt(3)
	v_add_f32_e32 v26, v26, v116
	v_add_f32_e32 v26, v26, v117
	s_waitcnt lgkmcnt(3)
	v_add_f32_e32 v22, v26, v120
	v_add_f32_e32 v22, v22, v121
	ds_read2st64_b32 v[116:117], v247 offset0:18 offset1:22
	v_fmamk_f32 v22, v22, 0x3c000000, v1
	v_mul_f32_e32 v26, 0x4b800000, v22
	v_cmp_gt_f32_e32 vcc, s33, v22
	s_waitcnt lgkmcnt(4)
	v_lshlrev_b32_e32 v23, 16, v242
	v_cndmask_b32_e32 v22, v22, v26, vcc
	v_mul_f32_e32 v26, 0xbfb8aa3b, v23
	v_exp_f32_e32 v26, v26
	v_rsq_f32_e32 v22, v22
	v_add_f32_e32 v26, 1.0, v26
	v_rcp_f32_e32 v26, v26
	v_mul_f32_e32 v27, 0x45800000, v22
	v_cndmask_b32_e32 v22, v22, v27, vcc
	v_mul_f32_e32 v22, v24, v22
	v_mul_f32_e32 v22, v99, v22
	v_mul_f32_e32 v23, v26, v23
	v_mul_f32_e32 v22, v23, v22
	v_cvt_pk_bf16_f32 v24, v22, v195
	ds_read2st64_b32 v[120:121], v247 offset0:26 offset1:30
	ds_read_u16 v242, v62 offset:46200
	ds_read2st64_b32 v[132:133], v248 offset0:2 offset1:6
	ds_write_b16 v87, v24 offset:8464
	s_waitcnt lgkmcnt(8)
; #define LAS __attribute__((address_space(3)))
; __device__ __forceinline__ float bf2f(unsigned short b) { return __uint_as_float(((unsigned)b) << 16); }
; __device__ __forceinline__ unsigned short f2bf(float f) { return (unsigned short)(cvt_pk_bf16(f, 0.f) & 0xffffu); }
; __device__ void gla_C(const Params& P, int l, int item, LAS unsigned char* lds) {
;     ...
;     for (int rt = 0; rt < 16; ++rt)
; #pragma unroll
;         for (int jj = 0; jj < 4; ++jj) { const int t = rt * 16 + 4 * g + jj; float tot = 0.f;
; #pragma unroll
;             for (int ww = 0; ww < 8; ++ww) tot += SSQ[ww * 256 + t];
;             const float rs = rsqrtf(tot * (1.0f / 128.0f) + EPS);
;             const float gt = bf2f(*(const LAS unsigned short*)(GTL + t * 264 + (16 * w + c) * 2));
;             *(LAS unsigned short*)(OT + t * 272 + (16 * w + c) * 2) = f2bf(O[rt][jj] * rs * ng * (gt * __builtin_amdgcn_rcpf(1.0f + __expf(-gt)))); }
	v_add_f32_e32 v22, 0, v126
	v_add_f32_e32 v24, v22, v127
	ds_read2st64_b32 v[126:127], v248 offset0:10 offset1:14
	s_waitcnt lgkmcnt(9)
	v_add_f32_e32 v24, v24, v128
	v_add_f32_e32 v24, v24, v129
	s_waitcnt lgkmcnt(9)
	v_add_f32_e32 v24, v24, v118
	v_add_f32_e32 v24, v24, v119
	s_waitcnt lgkmcnt(1)
	v_add_f32_e32 v22, v24, v122
	v_add_f32_e32 v22, v22, v123
	ds_read2st64_b32 v[118:119], v248 offset0:18 offset1:22
	v_fmamk_f32 v22, v22, 0x3c000000, v1
	v_mul_f32_e32 v24, 0x4b800000, v22
	v_cmp_gt_f32_e32 vcc, s33, v22
	s_waitcnt lgkmcnt(2)
	v_lshlrev_b32_e32 v23, 16, v243
	v_cndmask_b32_e32 v22, v22, v24, vcc
	v_mul_f32_e32 v24, 0xbfb8aa3b, v23
	v_exp_f32_e32 v24, v24
	v_rsq_f32_e32 v22, v22
	v_add_f32_e32 v24, 1.0, v24
	v_rcp_f32_e32 v24, v24
	v_mul_f32_e32 v26, 0x45800000, v22
	v_cndmask_b32_e32 v22, v22, v26, vcc
	v_mul_f32_e32 v22, v25, v22
	v_mul_f32_e32 v22, v99, v22
	v_mul_f32_e32 v23, v24, v23
	v_mul_f32_e32 v22, v23, v22
	v_cvt_pk_bf16_f32 v24, v22, v195
	ds_read2st64_b32 v[122:123], v248 offset0:26 offset1:30
	ds_write_b16 v87, v24 offset:8736
	ds_read_u16 v243, v62 offset:46464
	ds_read2st64_b32 v[128:129], v249 offset0:2 offset1:6
	s_waitcnt lgkmcnt(6)
	v_add_f32_e32 v22, 0, v130
	v_add_f32_e32 v28, v22, v131
	ds_read2st64_b32 v[130:131], v249 offset0:10 offset1:14
	s_waitcnt lgkmcnt(3)
	v_add_f32_e32 v24, v28, v124
	v_add_f32_e32 v24, v24, v125
	s_waitcnt lgkmcnt(3)
	v_add_f32_e32 v24, v24, v116
	v_add_f32_e32 v24, v24, v117
	s_waitcnt lgkmcnt(3)
	v_add_f32_e32 v22, v24, v120
	v_add_f32_e32 v22, v22, v121
	ds_read2st64_b32 v[116:117], v249 offset0:18 offset1:22
	v_fmamk_f32 v22, v22, 0x3c000000, v1
	v_mul_f32_e32 v24, 0x4b800000, v22
	v_cmp_gt_f32_e32 vcc, s33, v22
	s_waitcnt lgkmcnt(4)
	v_lshlrev_b32_e32 v23, 16, v242
	v_cndmask_b32_e32 v22, v22, v24, vcc
	v_mul_f32_e32 v24, 0xbfb8aa3b, v23
	v_exp_f32_e32 v24, v24
	v_rsq_f32_e32 v22, v22
	v_add_f32_e32 v24, 1.0, v24
	v_rcp_f32_e32 v24, v24
	v_mul_f32_e32 v25, 0x45800000, v22
	v_cndmask_b32_e32 v22, v22, v25, vcc
	v_mul_f32_e32 v18, v18, v22
	v_mul_f32_e32 v18, v99, v18
	v_mul_f32_e32 v22, v24, v23
	v_mul_f32_e32 v18, v22, v18
	v_cvt_pk_bf16_f32 v18, v18, v195
	ds_read2st64_b32 v[120:121], v249 offset0:26 offset1:30
	ds_read_u16 v242, v62 offset:46728
	ds_read2st64_b32 v[124:125], v236 offset0:2 offset1:6
	ds_write_b16 v87, v18 offset:12272
	s_waitcnt lgkmcnt(8)
	v_add_f32_e32 v18, 0, v132
	v_add_f32_e32 v18, v18, v133
	ds_read2st64_b32 v[132:133], v236 offset0:10 offset1:14
	s_waitcnt lgkmcnt(9)
	v_add_f32_e32 v18, v18, v126
	v_add_f32_e32 v18, v18, v127
	s_waitcnt lgkmcnt(9)
	v_add_f32_e32 v18, v18, v118
	v_add_f32_e32 v18, v18, v119
	s_waitcnt lgkmcnt(1)
	v_add_f32_e32 v18, v18, v122
	ds_read2st64_b32 v[118:119], v236 offset0:18 offset1:22
	v_add_f32_e32 v18, v18, v123
	v_fmamk_f32 v18, v18, 0x3c000000, v1
	v_mul_f32_e32 v23, 0x4b800000, v18
	v_cmp_gt_f32_e32 vcc, s33, v18
	s_waitcnt lgkmcnt(2)
	v_lshlrev_b32_e32 v22, 16, v243
	v_cndmask_b32_e32 v18, v18, v23, vcc
	v_mul_f32_e32 v23, 0xbfb8aa3b, v22
	v_exp_f32_e32 v23, v23
	v_rsq_f32_e32 v18, v18
	v_add_f32_e32 v23, 1.0, v23
	v_rcp_f32_e32 v23, v23
	v_mul_f32_e32 v24, 0x45800000, v18
	v_cndmask_b32_e32 v18, v18, v24, vcc
	v_mul_f32_e32 v18, v19, v18
	v_mul_f32_e32 v18, v99, v18
	v_mul_f32_e32 v19, v23, v22
	v_mul_f32_e32 v18, v19, v18
	v_cvt_pk_bf16_f32 v22, v18, v195
	ds_read2st64_b32 v[122:123], v236 offset0:26 offset1:30
	ds_write_b16 v87, v22 offset:12544
	ds_read_u16 v243, v62 offset:46992
	ds_read2st64_b32 v[126:127], v66 offset0:3 offset1:7
	s_waitcnt lgkmcnt(6)
	v_add_f32_e32 v18, 0, v128
	v_add_f32_e32 v26, v18, v129
	ds_read2st64_b32 v[128:129], v66 offset0:11 offset1:15
	s_waitcnt lgkmcnt(3)
	v_add_f32_e32 v22, v26, v130
	v_add_f32_e32 v22, v22, v131
	s_waitcnt lgkmcnt(3)
	v_add_f32_e32 v22, v22, v116
	v_add_f32_e32 v22, v22, v117
	s_waitcnt lgkmcnt(3)
	v_add_f32_e32 v18, v22, v120
	v_add_f32_e32 v18, v18, v121
	ds_read2st64_b32 v[116:117], v66 offset0:19 offset1:23
	v_fmamk_f32 v18, v18, 0x3c000000, v1
	v_mul_f32_e32 v22, 0x4b800000, v18
	v_cmp_gt_f32_e32 vcc, s33, v18
	v_add_u32_e32 v26, 0, v194
	s_waitcnt lgkmcnt(4)
	v_lshlrev_b32_e32 v19, 16, v242
	v_cndmask_b32_e32 v18, v18, v22, vcc
	v_mul_f32_e32 v22, 0xbfb8aa3b, v19
	v_exp_f32_e32 v22, v22
	v_rsq_f32_e32 v18, v18
	v_add_f32_e32 v22, 1.0, v22
	v_rcp_f32_e32 v22, v22
	v_mul_f32_e32 v23, 0x45800000, v18
	v_cndmask_b32_e32 v18, v18, v23, vcc
	v_mul_f32_e32 v18, v20, v18
	v_mul_f32_e32 v18, v99, v18
	v_mul_f32_e32 v19, v22, v19
	v_mul_f32_e32 v18, v19, v18
	v_cvt_pk_bf16_f32 v20, v18, v195
	ds_read2st64_b32 v[120:121], v66 offset0:27 offset1:31
	ds_read_u16 v242, v62 offset:50424
	ds_read2st64_b32 v[130:131], v158 offset0:3 offset1:7
	ds_write_b16 v86, v20 offset:8192
	s_waitcnt lgkmcnt(8)
	v_add_f32_e32 v18, 0, v124
	v_add_f32_e32 v20, v18, v125
	ds_read2st64_b32 v[124:125], v158 offset0:11 offset1:15
	s_waitcnt lgkmcnt(9)
	v_add_f32_e32 v20, v20, v132
	v_add_f32_e32 v20, v20, v133
	s_waitcnt lgkmcnt(9)
	v_add_f32_e32 v20, v20, v118
	v_add_f32_e32 v20, v20, v119
	s_waitcnt lgkmcnt(1)
	v_add_f32_e32 v18, v20, v122
	v_add_f32_e32 v18, v18, v123
	ds_read2st64_b32 v[118:119], v158 offset0:19 offset1:23
	v_fmamk_f32 v18, v18, 0x3c000000, v1
	v_mul_f32_e32 v20, 0x4b800000, v18
	v_cmp_gt_f32_e32 vcc, s33, v18
	s_waitcnt lgkmcnt(2)
	v_lshlrev_b32_e32 v19, 16, v243
	v_cndmask_b32_e32 v18, v18, v20, vcc
	v_mul_f32_e32 v20, 0xbfb8aa3b, v19
	v_exp_f32_e32 v20, v20
	v_rsq_f32_e32 v18, v18
	v_add_f32_e32 v20, 1.0, v20
	v_rcp_f32_e32 v20, v20
	v_mul_f32_e32 v22, 0x45800000, v18
	v_cndmask_b32_e32 v18, v18, v22, vcc
	v_mul_f32_e32 v18, v21, v18
	v_mul_f32_e32 v18, v99, v18
	v_mul_f32_e32 v19, v20, v19
	v_mul_f32_e32 v18, v19, v18
	v_cvt_pk_bf16_f32 v20, v18, v195
	ds_read2st64_b32 v[122:123], v158 offset0:27 offset1:31
	ds_write_b16 v86, v20 offset:8464
	ds_read_u16 v243, v62 offset:50688
	ds_read2st64_b32 v[132:133], v159 offset0:3 offset1:7
	s_waitcnt lgkmcnt(6)
; #define LAS __attribute__((address_space(3)))
; __device__ __forceinline__ float bf2f(unsigned short b) { return __uint_as_float(((unsigned)b) << 16); }
; __device__ __forceinline__ unsigned short f2bf(float f) { return (unsigned short)(cvt_pk_bf16(f, 0.f) & 0xffffu); }
; __device__ void gla_C(const Params& P, int l, int item, LAS unsigned char* lds) {
;     ...
;     for (int rt = 0; rt < 16; ++rt)
; #pragma unroll
;         for (int jj = 0; jj < 4; ++jj) { const int t = rt * 16 + 4 * g + jj; float tot = 0.f;
; #pragma unroll
;             for (int ww = 0; ww < 8; ++ww) tot += SSQ[ww * 256 + t];
;             const float rs = rsqrtf(tot * (1.0f / 128.0f) + EPS);
;             const float gt = bf2f(*(const LAS unsigned short*)(GTL + t * 264 + (16 * w + c) * 2));
;             *(LAS unsigned short*)(OT + t * 272 + (16 * w + c) * 2) = f2bf(O[rt][jj] * rs * ng * (gt * __builtin_amdgcn_rcpf(1.0f + __expf(-gt)))); }
	v_add_f32_e32 v18, 0, v126
	v_add_f32_e32 v24, v18, v127
	ds_read2st64_b32 v[126:127], v159 offset0:11 offset1:15
	s_waitcnt lgkmcnt(3)
	v_add_f32_e32 v20, v24, v128
	v_add_f32_e32 v20, v20, v129
	s_waitcnt lgkmcnt(3)
	v_add_f32_e32 v20, v20, v116
	v_add_f32_e32 v20, v20, v117
	s_waitcnt lgkmcnt(3)
	v_add_f32_e32 v18, v20, v120
	v_add_f32_e32 v18, v18, v121
	ds_read2st64_b32 v[116:117], v159 offset0:19 offset1:23
	v_fmamk_f32 v18, v18, 0x3c000000, v1
	v_mul_f32_e32 v20, 0x4b800000, v18
	v_cmp_gt_f32_e32 vcc, s33, v18
	s_waitcnt lgkmcnt(4)
	v_lshlrev_b32_e32 v19, 16, v242
	v_cndmask_b32_e32 v18, v18, v20, vcc
	v_mul_f32_e32 v20, 0xbfb8aa3b, v19
	v_exp_f32_e32 v20, v20
	v_rsq_f32_e32 v18, v18
	v_add_f32_e32 v20, 1.0, v20
	v_rcp_f32_e32 v20, v20
	v_mul_f32_e32 v21, 0x45800000, v18
	v_cndmask_b32_e32 v18, v18, v21, vcc
	v_mul_f32_e32 v14, v14, v18
	v_mul_f32_e32 v14, v99, v14
	v_mul_f32_e32 v18, v20, v19
	v_mul_f32_e32 v14, v18, v14
	v_cvt_pk_bf16_f32 v14, v14, v195
	ds_read2st64_b32 v[120:121], v159 offset0:27 offset1:31
	ds_read_u16 v242, v62 offset:50952
	ds_read2st64_b32 v[128:129], v160 offset0:3 offset1:7
	ds_write_b16 v86, v14 offset:12000
	s_waitcnt lgkmcnt(8)
	v_add_f32_e32 v14, 0, v130
	v_add_f32_e32 v14, v14, v131
	ds_read2st64_b32 v[130:131], v160 offset0:11 offset1:15
	s_waitcnt lgkmcnt(9)
	v_add_f32_e32 v14, v14, v124
	v_add_f32_e32 v14, v14, v125
	s_waitcnt lgkmcnt(9)
	v_add_f32_e32 v14, v14, v118
	v_add_f32_e32 v14, v14, v119
	s_waitcnt lgkmcnt(1)
	v_add_f32_e32 v14, v14, v122
	ds_read2st64_b32 v[118:119], v160 offset0:19 offset1:23
	v_add_f32_e32 v14, v14, v123
	v_fmamk_f32 v14, v14, 0x3c000000, v1
	v_mul_f32_e32 v19, 0x4b800000, v14
	v_cmp_gt_f32_e32 vcc, s33, v14
	s_waitcnt lgkmcnt(2)
	v_lshlrev_b32_e32 v18, 16, v243
	v_cndmask_b32_e32 v14, v14, v19, vcc
	v_mul_f32_e32 v19, 0xbfb8aa3b, v18
	v_exp_f32_e32 v19, v19
	v_rsq_f32_e32 v14, v14
	v_add_f32_e32 v19, 1.0, v19
	v_rcp_f32_e32 v19, v19
	v_mul_f32_e32 v20, 0x45800000, v14
	v_cndmask_b32_e32 v14, v14, v20, vcc
	v_mul_f32_e32 v14, v15, v14
	v_mul_f32_e32 v14, v99, v14
	v_mul_f32_e32 v15, v19, v18
	v_mul_f32_e32 v14, v15, v14
	v_cvt_pk_bf16_f32 v18, v14, v195
	ds_read2st64_b32 v[122:123], v160 offset0:27 offset1:31
	ds_write_b16 v86, v18 offset:12272
	ds_read_u16 v243, v62 offset:51216
	ds_read2st64_b32 v[124:125], v161 offset0:3 offset1:7
	s_waitcnt lgkmcnt(6)
	v_add_f32_e32 v14, 0, v132
	v_add_f32_e32 v22, v14, v133
	ds_read2st64_b32 v[132:133], v161 offset0:11 offset1:15
	s_waitcnt lgkmcnt(3)
	v_add_f32_e32 v18, v22, v126
	v_add_f32_e32 v18, v18, v127
	s_waitcnt lgkmcnt(3)
	v_add_f32_e32 v18, v18, v116
	v_add_f32_e32 v18, v18, v117
	s_waitcnt lgkmcnt(3)
	v_add_f32_e32 v14, v18, v120
	v_add_f32_e32 v14, v14, v121
	ds_read2st64_b32 v[116:117], v161 offset0:19 offset1:23
	v_fmamk_f32 v14, v14, 0x3c000000, v1
	v_mul_f32_e32 v18, 0x4b800000, v14
	v_cmp_gt_f32_e32 vcc, s33, v14
	s_waitcnt lgkmcnt(4)
	v_lshlrev_b32_e32 v15, 16, v242
	v_cndmask_b32_e32 v14, v14, v18, vcc
	v_mul_f32_e32 v18, 0xbfb8aa3b, v15
	v_exp_f32_e32 v18, v18
	v_rsq_f32_e32 v14, v14
	v_add_f32_e32 v18, 1.0, v18
	v_rcp_f32_e32 v18, v18
	v_mul_f32_e32 v19, 0x45800000, v14
	v_cndmask_b32_e32 v14, v14, v19, vcc
	v_mul_f32_e32 v14, v16, v14
	v_mul_f32_e32 v14, v99, v14
	v_mul_f32_e32 v15, v18, v15
	v_mul_f32_e32 v14, v15, v14
	v_cvt_pk_bf16_f32 v16, v14, v195
	ds_read2st64_b32 v[120:121], v161 offset0:27 offset1:31
	ds_read_u16 v242, v62 offset:54648
	ds_read2st64_b32 v[126:127], v162 offset0:3 offset1:7
	ds_write_b16 v86, v16 offset:12544
	s_waitcnt lgkmcnt(8)
	v_add_f32_e32 v14, 0, v128
	v_add_f32_e32 v16, v14, v129
	ds_read2st64_b32 v[128:129], v162 offset0:11 offset1:15
	s_waitcnt lgkmcnt(9)
	v_add_f32_e32 v16, v16, v130
	v_add_f32_e32 v16, v16, v131
	s_waitcnt lgkmcnt(9)
	v_add_f32_e32 v16, v16, v118
	v_add_f32_e32 v16, v16, v119
	s_waitcnt lgkmcnt(1)
	v_add_f32_e32 v14, v16, v122
	v_add_f32_e32 v14, v14, v123
	ds_read2st64_b32 v[118:119], v162 offset0:19 offset1:23
	v_fmamk_f32 v14, v14, 0x3c000000, v1
	v_mul_f32_e32 v16, 0x4b800000, v14
	v_cmp_gt_f32_e32 vcc, s33, v14
	s_waitcnt lgkmcnt(2)
	v_lshlrev_b32_e32 v15, 16, v243
	v_cndmask_b32_e32 v14, v14, v16, vcc
	v_mul_f32_e32 v16, 0xbfb8aa3b, v15
	v_exp_f32_e32 v16, v16
	v_rsq_f32_e32 v14, v14
	v_add_f32_e32 v16, 1.0, v16
	v_rcp_f32_e32 v16, v16
	v_mul_f32_e32 v18, 0x45800000, v14
	v_cndmask_b32_e32 v14, v14, v18, vcc
	v_mul_f32_e32 v14, v17, v14
	v_mul_f32_e32 v14, v99, v14
	v_mul_f32_e32 v15, v16, v15
	v_mul_f32_e32 v14, v15, v14
	v_cvt_pk_bf16_f32 v16, v14, v195
	ds_read2st64_b32 v[122:123], v162 offset0:27 offset1:31
	ds_write_b16 v85, v16 offset:8192
	ds_read_u16 v243, v62 offset:54912
	ds_read2st64_b32 v[130:131], v163 offset0:3 offset1:7
	s_waitcnt lgkmcnt(6)
	v_add_f32_e32 v14, 0, v124
	v_add_f32_e32 v20, v14, v125
	ds_read2st64_b32 v[124:125], v163 offset0:11 offset1:15
	s_waitcnt lgkmcnt(3)
	v_add_f32_e32 v16, v20, v132
	v_add_f32_e32 v16, v16, v133
	s_waitcnt lgkmcnt(3)
	v_add_f32_e32 v16, v16, v116
	v_add_f32_e32 v16, v16, v117
	s_waitcnt lgkmcnt(3)
	v_add_f32_e32 v14, v16, v120
	v_add_f32_e32 v14, v14, v121
	ds_read2st64_b32 v[116:117], v163 offset0:19 offset1:23
	v_fmamk_f32 v14, v14, 0x3c000000, v1
	v_mul_f32_e32 v16, 0x4b800000, v14
	v_cmp_gt_f32_e32 vcc, s33, v14
	s_waitcnt lgkmcnt(4)
	v_lshlrev_b32_e32 v15, 16, v242
	v_cndmask_b32_e32 v14, v14, v16, vcc
	v_mul_f32_e32 v16, 0xbfb8aa3b, v15
	v_exp_f32_e32 v16, v16
	v_rsq_f32_e32 v14, v14
	v_add_f32_e32 v16, 1.0, v16
	v_rcp_f32_e32 v16, v16
	v_mul_f32_e32 v17, 0x45800000, v14
	v_cndmask_b32_e32 v14, v14, v17, vcc
	v_mul_f32_e32 v10, v10, v14
	v_mul_f32_e32 v10, v99, v10
	v_mul_f32_e32 v14, v16, v15
	v_mul_f32_e32 v10, v14, v10
	v_cvt_pk_bf16_f32 v10, v10, v195
	ds_read2st64_b32 v[120:121], v163 offset0:27 offset1:31
	ds_read_u16 v242, v62 offset:55176
	ds_read2st64_b32 v[132:133], v164 offset0:3 offset1:7
	ds_write_b16 v85, v10 offset:11728
	s_waitcnt lgkmcnt(8)
; #define LAS __attribute__((address_space(3)))
; __device__ __forceinline__ float bf2f(unsigned short b) { return __uint_as_float(((unsigned)b) << 16); }
; __device__ __forceinline__ unsigned short f2bf(float f) { return (unsigned short)(cvt_pk_bf16(f, 0.f) & 0xffffu); }
; __device__ void gla_C(const Params& P, int l, int item, LAS unsigned char* lds) {
;     ...
; #pragma unroll
;     for (int rt = 0; rt < 16; ++rt)
; #pragma unroll
;         for (int jj = 0; jj < 4; ++jj) { const int t = rt * 16 + 4 * g + jj; float tot = 0.f;
; #pragma unroll
;             for (int ww = 0; ww < 8; ++ww) tot += SSQ[ww * 256 + t];
;             const float rs = rsqrtf(tot * (1.0f / 128.0f) + EPS);
;             const float gt = bf2f(*(const LAS unsigned short*)(GTL + t * 264 + (16 * w + c) * 2));
;             *(LAS unsigned short*)(OT + t * 272 + (16 * w + c) * 2) = f2bf(O[rt][jj] * rs * ng * (gt * __builtin_amdgcn_rcpf(1.0f + __expf(-gt)))); }
	v_add_f32_e32 v10, 0, v126
	v_add_f32_e32 v10, v10, v127
	ds_read2st64_b32 v[126:127], v164 offset0:11 offset1:15
	s_waitcnt lgkmcnt(9)
	v_add_f32_e32 v10, v10, v128
	v_add_f32_e32 v10, v10, v129
	s_waitcnt lgkmcnt(9)
	v_add_f32_e32 v10, v10, v118
	v_add_f32_e32 v10, v10, v119
	s_waitcnt lgkmcnt(1)
	v_add_f32_e32 v10, v10, v122
	ds_read2st64_b32 v[118:119], v164 offset0:19 offset1:23
	v_add_f32_e32 v10, v10, v123
	v_fmamk_f32 v10, v10, 0x3c000000, v1
	v_mul_f32_e32 v15, 0x4b800000, v10
	v_cmp_gt_f32_e32 vcc, s33, v10
	s_waitcnt lgkmcnt(2)
	v_lshlrev_b32_e32 v14, 16, v243
	v_cndmask_b32_e32 v10, v10, v15, vcc
	v_mul_f32_e32 v15, 0xbfb8aa3b, v14
	v_exp_f32_e32 v15, v15
	v_rsq_f32_e32 v10, v10
	v_add_f32_e32 v15, 1.0, v15
	v_rcp_f32_e32 v15, v15
	v_mul_f32_e32 v16, 0x45800000, v10
	v_cndmask_b32_e32 v10, v10, v16, vcc
	v_mul_f32_e32 v10, v11, v10
	v_mul_f32_e32 v10, v99, v10
	v_mul_f32_e32 v11, v15, v14
	v_mul_f32_e32 v10, v11, v10
	v_cvt_pk_bf16_f32 v14, v10, v195
	ds_read2st64_b32 v[122:123], v164 offset0:27 offset1:31
	ds_write_b16 v85, v14 offset:12000
	ds_read_u16 v243, v62 offset:55440
	ds_read2st64_b32 v[128:129], v165 offset0:3 offset1:7
	s_waitcnt lgkmcnt(6)
	v_add_f32_e32 v10, 0, v130
	v_add_f32_e32 v18, v10, v131
	ds_read2st64_b32 v[130:131], v165 offset0:11 offset1:15
	s_waitcnt lgkmcnt(3)
	v_add_f32_e32 v14, v18, v124
	v_add_f32_e32 v14, v14, v125
	s_waitcnt lgkmcnt(3)
	v_add_f32_e32 v14, v14, v116
	v_add_f32_e32 v14, v14, v117
	s_waitcnt lgkmcnt(3)
	v_add_f32_e32 v10, v14, v120
	v_add_f32_e32 v10, v10, v121
	ds_read2st64_b32 v[116:117], v165 offset0:19 offset1:23
	v_fmamk_f32 v10, v10, 0x3c000000, v1
	v_mul_f32_e32 v14, 0x4b800000, v10
	v_cmp_gt_f32_e32 vcc, s33, v10
	s_waitcnt lgkmcnt(4)
	v_lshlrev_b32_e32 v11, 16, v242
	v_cndmask_b32_e32 v10, v10, v14, vcc
	v_mul_f32_e32 v14, 0xbfb8aa3b, v11
	v_exp_f32_e32 v14, v14
	v_rsq_f32_e32 v10, v10
	v_add_f32_e32 v14, 1.0, v14
	v_rcp_f32_e32 v14, v14
	v_mul_f32_e32 v15, 0x45800000, v10
	v_cndmask_b32_e32 v10, v10, v15, vcc
	v_mul_f32_e32 v10, v12, v10
	v_mul_f32_e32 v10, v99, v10
	v_mul_f32_e32 v11, v14, v11
	v_mul_f32_e32 v10, v11, v10
	v_cvt_pk_bf16_f32 v12, v10, v195
	ds_read2st64_b32 v[120:121], v165 offset0:27 offset1:31
	ds_read_u16 v242, v62 offset:58872
	ds_read2st64_b32 v[124:125], v244 offset0:3 offset1:7
	ds_write_b16 v85, v12 offset:12272
	s_waitcnt lgkmcnt(8)
	v_add_f32_e32 v10, 0, v132
	v_add_f32_e32 v12, v10, v133
	ds_read2st64_b32 v[132:133], v244 offset0:11 offset1:15
	s_waitcnt lgkmcnt(9)
	v_add_f32_e32 v12, v12, v126
	v_add_f32_e32 v12, v12, v127
	s_waitcnt lgkmcnt(9)
	v_add_f32_e32 v12, v12, v118
	v_add_f32_e32 v12, v12, v119
	s_waitcnt lgkmcnt(1)
	v_add_f32_e32 v10, v12, v122
	v_add_f32_e32 v10, v10, v123
	ds_read2st64_b32 v[118:119], v244 offset0:19 offset1:23
	v_fmamk_f32 v10, v10, 0x3c000000, v1
	v_mul_f32_e32 v12, 0x4b800000, v10
	v_cmp_gt_f32_e32 vcc, s33, v10
	s_waitcnt lgkmcnt(2)
	v_lshlrev_b32_e32 v11, 16, v243
	v_cndmask_b32_e32 v10, v10, v12, vcc
	v_mul_f32_e32 v12, 0xbfb8aa3b, v11
	v_exp_f32_e32 v12, v12
	v_rsq_f32_e32 v10, v10
	v_add_f32_e32 v12, 1.0, v12
	v_rcp_f32_e32 v12, v12
	v_mul_f32_e32 v14, 0x45800000, v10
	v_cndmask_b32_e32 v10, v10, v14, vcc
	v_mul_f32_e32 v10, v13, v10
	v_mul_f32_e32 v10, v99, v10
	v_mul_f32_e32 v11, v12, v11
	v_mul_f32_e32 v10, v11, v10
	v_cvt_pk_bf16_f32 v12, v10, v195
	ds_read2st64_b32 v[122:123], v244 offset0:27 offset1:31
	ds_write_b16 v85, v12 offset:12544
	ds_read_u16 v243, v62 offset:59136
	ds_read2st64_b32 v[126:127], v245 offset0:3 offset1:7
	s_waitcnt lgkmcnt(6)
	v_add_f32_e32 v10, 0, v128
	v_add_f32_e32 v16, v10, v129
	ds_read2st64_b32 v[128:129], v245 offset0:11 offset1:15
	s_waitcnt lgkmcnt(3)
	v_add_f32_e32 v12, v16, v130
	v_add_f32_e32 v12, v12, v131
	s_waitcnt lgkmcnt(3)
	v_add_f32_e32 v12, v12, v116
	v_add_f32_e32 v12, v12, v117
	s_waitcnt lgkmcnt(3)
	v_add_f32_e32 v10, v12, v120
	v_add_f32_e32 v10, v10, v121
	ds_read2st64_b32 v[116:117], v245 offset0:19 offset1:23
	v_fmamk_f32 v10, v10, 0x3c000000, v1
	v_mul_f32_e32 v12, 0x4b800000, v10
	v_cmp_gt_f32_e32 vcc, s33, v10
	s_waitcnt lgkmcnt(4)
	v_lshlrev_b32_e32 v11, 16, v242
	v_cndmask_b32_e32 v10, v10, v12, vcc
	v_mul_f32_e32 v12, 0xbfb8aa3b, v11
	v_exp_f32_e32 v12, v12
	v_rsq_f32_e32 v10, v10
	v_add_f32_e32 v12, 1.0, v12
	v_rcp_f32_e32 v12, v12
	v_mul_f32_e32 v13, 0x45800000, v10
	v_cndmask_b32_e32 v10, v10, v13, vcc
	v_mul_f32_e32 v6, v6, v10
	v_mul_f32_e32 v6, v99, v6
	v_mul_f32_e32 v10, v12, v11
	v_mul_f32_e32 v6, v10, v6
	v_cvt_pk_bf16_f32 v6, v6, v195
	ds_read2st64_b32 v[120:121], v245 offset0:27 offset1:31
	ds_read_u16 v242, v62 offset:59400
	ds_read2st64_b32 v[130:131], v246 offset0:3 offset1:7
	ds_write_b16 v84, v6 offset:8192
	s_waitcnt lgkmcnt(8)
	v_add_f32_e32 v6, 0, v124
	v_add_f32_e32 v6, v6, v125
	ds_read2st64_b32 v[124:125], v246 offset0:11 offset1:15
	s_waitcnt lgkmcnt(9)
	v_add_f32_e32 v6, v6, v132
	v_add_f32_e32 v6, v6, v133
	s_waitcnt lgkmcnt(9)
	v_add_f32_e32 v6, v6, v118
	v_add_f32_e32 v6, v6, v119
	s_waitcnt lgkmcnt(1)
	v_add_f32_e32 v6, v6, v122
	ds_read2st64_b32 v[118:119], v246 offset0:19 offset1:23
	v_add_f32_e32 v6, v6, v123
	v_fmamk_f32 v6, v6, 0x3c000000, v1
	v_mul_f32_e32 v11, 0x4b800000, v6
	v_cmp_gt_f32_e32 vcc, s33, v6
	s_waitcnt lgkmcnt(2)
	v_lshlrev_b32_e32 v10, 16, v243
	v_cndmask_b32_e32 v6, v6, v11, vcc
	v_mul_f32_e32 v11, 0xbfb8aa3b, v10
	v_exp_f32_e32 v11, v11
	v_rsq_f32_e32 v6, v6
	v_add_f32_e32 v11, 1.0, v11
	v_rcp_f32_e32 v11, v11
	v_mul_f32_e32 v12, 0x45800000, v6
	v_cndmask_b32_e32 v6, v6, v12, vcc
	v_mul_f32_e32 v6, v7, v6
	v_mul_f32_e32 v6, v99, v6
	v_mul_f32_e32 v7, v11, v10
	v_mul_f32_e32 v6, v7, v6
	v_cvt_pk_bf16_f32 v10, v6, v195
	ds_read2st64_b32 v[122:123], v246 offset0:27 offset1:31
	ds_write_b16 v84, v10 offset:8464
	ds_read_u16 v243, v62 offset:59664
	ds_read2st64_b32 v[132:133], v247 offset0:3 offset1:7
	s_waitcnt lgkmcnt(6)
; #define LAS __attribute__((address_space(3)))
; __device__ __forceinline__ float bf2f(unsigned short b) { return __uint_as_float(((unsigned)b) << 16); }
; __device__ __forceinline__ unsigned short f2bf(float f) { return (unsigned short)(cvt_pk_bf16(f, 0.f) & 0xffffu); }
; __device__ void gla_C(const Params& P, int l, int item, LAS unsigned char* lds) {
;     ...
; #pragma unroll
;     for (int rt = 0; rt < 16; ++rt)
; #pragma unroll
;         for (int jj = 0; jj < 4; ++jj) { const int t = rt * 16 + 4 * g + jj; float tot = 0.f;
; #pragma unroll
;             for (int ww = 0; ww < 8; ++ww) tot += SSQ[ww * 256 + t];
;             const float rs = rsqrtf(tot * (1.0f / 128.0f) + EPS);
;             const float gt = bf2f(*(const LAS unsigned short*)(GTL + t * 264 + (16 * w + c) * 2));
;             *(LAS unsigned short*)(OT + t * 272 + (16 * w + c) * 2) = f2bf(O[rt][jj] * rs * ng * (gt * __builtin_amdgcn_rcpf(1.0f + __expf(-gt)))); }
;     __syncthreads();
	v_add_f32_e32 v6, 0, v126
	v_add_f32_e32 v14, v6, v127
	ds_read2st64_b32 v[126:127], v247 offset0:11 offset1:15
	s_waitcnt lgkmcnt(3)
	v_add_f32_e32 v10, v14, v128
	v_add_f32_e32 v10, v10, v129
	s_waitcnt lgkmcnt(3)
	v_add_f32_e32 v10, v10, v116
	v_add_f32_e32 v10, v10, v117
	s_waitcnt lgkmcnt(3)
	v_add_f32_e32 v6, v10, v120
	v_add_f32_e32 v6, v6, v121
	ds_read2st64_b32 v[116:117], v247 offset0:19 offset1:23
	v_fmamk_f32 v6, v6, 0x3c000000, v1
	v_mul_f32_e32 v10, 0x4b800000, v6
	v_cmp_gt_f32_e32 vcc, s33, v6
	s_waitcnt lgkmcnt(4)
	v_lshlrev_b32_e32 v7, 16, v242
	v_cndmask_b32_e32 v6, v6, v10, vcc
	v_mul_f32_e32 v10, 0xbfb8aa3b, v7
	v_exp_f32_e32 v10, v10
	v_rsq_f32_e32 v6, v6
	v_add_f32_e32 v10, 1.0, v10
	v_rcp_f32_e32 v10, v10
	v_mul_f32_e32 v11, 0x45800000, v6
	v_cndmask_b32_e32 v6, v6, v11, vcc
	v_mul_f32_e32 v6, v8, v6
	v_mul_f32_e32 v6, v99, v6
	v_mul_f32_e32 v7, v10, v7
	v_mul_f32_e32 v6, v7, v6
	v_cvt_pk_bf16_f32 v8, v6, v195
	ds_read2st64_b32 v[120:121], v247 offset0:27 offset1:31
	ds_read_u16 v242, v62 offset:63096
	ds_read2st64_b32 v[128:129], v248 offset0:3 offset1:7
	ds_write_b16 v84, v8 offset:8736
	s_waitcnt lgkmcnt(8)
	v_add_f32_e32 v6, 0, v130
	v_add_f32_e32 v8, v6, v131
	ds_read2st64_b32 v[130:131], v248 offset0:11 offset1:15
	s_waitcnt lgkmcnt(9)
	v_add_f32_e32 v8, v8, v124
	v_add_f32_e32 v8, v8, v125
	s_waitcnt lgkmcnt(9)
	v_add_f32_e32 v8, v8, v118
	v_add_f32_e32 v8, v8, v119
	s_waitcnt lgkmcnt(1)
	v_add_f32_e32 v6, v8, v122
	v_add_f32_e32 v6, v6, v123
	ds_read2st64_b32 v[118:119], v248 offset0:19 offset1:23
	v_fmamk_f32 v6, v6, 0x3c000000, v1
	v_mul_f32_e32 v8, 0x4b800000, v6
	v_cmp_gt_f32_e32 vcc, s33, v6
	s_waitcnt lgkmcnt(2)
	v_lshlrev_b32_e32 v7, 16, v243
	v_cndmask_b32_e32 v6, v6, v8, vcc
	v_mul_f32_e32 v8, 0xbfb8aa3b, v7
	v_exp_f32_e32 v8, v8
	v_rsq_f32_e32 v6, v6
	v_add_f32_e32 v8, 1.0, v8
	v_rcp_f32_e32 v8, v8
	v_mul_f32_e32 v10, 0x45800000, v6
	v_cndmask_b32_e32 v6, v6, v10, vcc
	v_mul_f32_e32 v6, v9, v6
	v_mul_f32_e32 v6, v99, v6
	v_mul_f32_e32 v7, v8, v7
	v_mul_f32_e32 v6, v7, v6
	v_cvt_pk_bf16_f32 v10, v6, v195
	ds_read2st64_b32 v[122:123], v248 offset0:27 offset1:31
	ds_write_b16 v84, v10 offset:9008
	ds_read_u16 v243, v62 offset:63360
	ds_read2st64_b32 v[124:125], v249 offset0:3 offset1:7
	v_mad_i64_i32 v[6:7], s[0:1], v156, s25, 0
	s_waitcnt lgkmcnt(6)
	v_add_f32_e32 v8, 0, v132
	v_add_f32_e32 v14, v8, v133
	ds_read2st64_b32 v[132:133], v249 offset0:11 offset1:15
	s_waitcnt lgkmcnt(3)
	v_add_f32_e32 v10, v14, v126
	v_add_f32_e32 v10, v10, v127
	s_waitcnt lgkmcnt(3)
	v_add_f32_e32 v10, v10, v116
	v_add_f32_e32 v10, v10, v117
	s_waitcnt lgkmcnt(3)
	v_add_f32_e32 v8, v10, v120
	v_add_f32_e32 v8, v8, v121
	ds_read2st64_b32 v[116:117], v249 offset0:19 offset1:23
	v_fmamk_f32 v8, v8, 0x3c000000, v1
	v_mul_f32_e32 v10, 0x4b800000, v8
	v_cmp_gt_f32_e32 vcc, s33, v8
	s_waitcnt lgkmcnt(4)
	v_lshlrev_b32_e32 v11, 16, v242
	v_cndmask_b32_e32 v8, v8, v10, vcc
	v_rsq_f32_e32 v10, v8
	v_mul_f32_e32 v8, 0xbfb8aa3b, v11
	v_exp_f32_e32 v12, v8
	v_mad_i64_i32 v[8:9], s[0:1], v155, s25, 0
	v_mul_f32_e32 v13, 0x45800000, v10
	v_add_f32_e32 v12, 1.0, v12
	v_rcp_f32_e32 v12, v12
	v_cndmask_b32_e32 v10, v10, v13, vcc
	v_mul_f32_e32 v2, v2, v10
	v_mul_f32_e32 v2, v99, v2
	v_mul_f32_e32 v10, v12, v11
	v_mul_f32_e32 v2, v10, v2
	v_cvt_pk_bf16_f32 v2, v2, v195
	ds_read2st64_b32 v[120:121], v249 offset0:27 offset1:31
	ds_read_u16 v242, v62 offset:63624
	ds_read2st64_b32 v[126:127], v236 offset0:3 offset1:7
	ds_write_b16 v84, v2 offset:12544
	v_lshl_add_u64 v[8:9], s[28:29], 0, v[8:9]
	s_waitcnt lgkmcnt(8)
	v_add_f32_e32 v2, 0, v128
	v_add_f32_e32 v2, v2, v129
	ds_read2st64_b32 v[128:129], v236 offset0:11 offset1:15
	s_waitcnt lgkmcnt(9)
	v_add_f32_e32 v2, v2, v130
	v_add_f32_e32 v2, v2, v131
	s_waitcnt lgkmcnt(9)
	v_add_f32_e32 v2, v2, v118
	v_add_f32_e32 v2, v2, v119
	s_waitcnt lgkmcnt(1)
	v_add_f32_e32 v2, v2, v122
	ds_read2st64_b32 v[118:119], v236 offset0:19 offset1:23
	v_add_f32_e32 v2, v2, v123
	v_fmamk_f32 v2, v2, 0x3c000000, v1
	v_mul_f32_e32 v13, 0x4b800000, v2
	v_cmp_gt_f32_e32 vcc, s33, v2
	s_waitcnt lgkmcnt(2)
	v_lshlrev_b32_e32 v14, 16, v243
	v_mul_f32_e32 v12, 0xbfb8aa3b, v14
	v_exp_f32_e32 v15, v12
	v_cndmask_b32_e32 v2, v2, v13, vcc
	v_rsq_f32_e32 v2, v2
	v_lshl_add_u64 v[8:9], v[8:9], 0, s[20:21]
	v_add_f32_e32 v15, 1.0, v15
	v_rcp_f32_e32 v15, v15
	v_mul_f32_e32 v16, 0x45800000, v2
	v_cndmask_b32_e32 v2, v2, v16, vcc
	v_mul_f32_e32 v2, v3, v2
	v_mul_f32_e32 v2, v99, v2
	v_mul_f32_e32 v3, v15, v14
	v_mul_f32_e32 v2, v3, v2
	v_cvt_pk_bf16_f32 v16, v2, v195
	ds_read2st64_b32 v[122:123], v236 offset0:27 offset1:31
	ds_write_b16 v84, v16 offset:12816
	ds_read_u16 v243, v62 offset:63888
	s_nop 0
	v_lshl_add_u64 v[8:9], v[8:9], 0, v[194:195]
	s_waitcnt lgkmcnt(5)
	v_add_f32_e32 v14, 0, v124
	v_add_f32_e32 v20, v14, v125
	s_nop 0
	s_waitcnt lgkmcnt(1)
	v_add_f32_e32 v16, v20, v132
	v_add_f32_e32 v16, v16, v133
	s_waitcnt lgkmcnt(1)
	v_add_f32_e32 v16, v16, v116
	v_add_f32_e32 v16, v16, v117
	s_waitcnt lgkmcnt(1)
	v_add_f32_e32 v14, v16, v120
	v_add_f32_e32 v14, v14, v121
	s_nop 0
	v_fmamk_f32 v14, v14, 0x3c000000, v1
	v_mul_f32_e32 v16, 0x4b800000, v14
	v_cmp_gt_f32_e32 vcc, s33, v14
	v_mad_i64_i32 v[10:11], s[0:1], v154, s25, 0
	s_waitcnt lgkmcnt(1)
	v_lshlrev_b32_e32 v15, 16, v242
	v_cndmask_b32_e32 v14, v14, v16, vcc
	v_mul_f32_e32 v16, 0xbfb8aa3b, v15
	v_exp_f32_e32 v16, v16
	v_rsq_f32_e32 v14, v14
	v_mad_i64_i32 v[12:13], s[0:1], v153, s25, 0
	v_add_f32_e32 v16, 1.0, v16
	v_rcp_f32_e32 v16, v16
	v_mul_f32_e32 v17, 0x45800000, v14
	v_cndmask_b32_e32 v14, v14, v17, vcc
	v_mul_f32_e32 v4, v4, v14
	v_mul_f32_e32 v4, v99, v4
	v_mul_f32_e32 v14, v16, v15
	v_mul_f32_e32 v4, v14, v4
	v_cvt_pk_bf16_f32 v4, v4, v195
	s_nop 0
	s_nop 0
	s_nop 0
	ds_write_b16 v84, v4 offset:13088
	v_mad_i64_i32 v[2:3], s[0:1], v152, s25, 0
	s_waitcnt lgkmcnt(2)
	v_add_f32_e32 v4, 0, v126
	v_add_f32_e32 v4, v4, v127
	s_nop 0
	s_waitcnt lgkmcnt(2)
	v_add_f32_e32 v4, v4, v128
	v_add_f32_e32 v4, v4, v129
	s_waitcnt lgkmcnt(2)
	v_add_f32_e32 v4, v4, v118
	v_add_f32_e32 v4, v4, v119
	s_waitcnt lgkmcnt(0)
	v_add_f32_e32 v4, v4, v122
	s_nop 0
	v_add_f32_e32 v4, v4, v123
	v_fmamk_f32 v4, v4, 0x3c000000, v1
	v_mul_f32_e32 v15, 0x4b800000, v4
	v_cmp_gt_f32_e32 vcc, s33, v4
	s_waitcnt lgkmcnt(0)
	v_lshlrev_b32_e32 v14, 16, v243
	v_lshl_add_u64 v[2:3], s[28:29], 0, v[2:3]
	v_cndmask_b32_e32 v4, v4, v15, vcc
	v_mul_f32_e32 v15, 0xbfb8aa3b, v14
	v_exp_f32_e32 v15, v15
	v_rsq_f32_e32 v4, v4
	v_lshl_add_u64 v[2:3], v[2:3], 0, s[20:21]
	v_mad_i64_i32 v[18:19], s[0:1], v151, s25, 0
	v_add_f32_e32 v15, 1.0, v15
	v_rcp_f32_e32 v15, v15
	v_mul_f32_e32 v16, 0x45800000, v4
	v_cndmask_b32_e32 v4, v4, v16, vcc
	v_mul_f32_e32 v4, v5, v4
	v_mul_f32_e32 v4, v99, v4
	v_mul_f32_e32 v5, v15, v14
	v_mul_f32_e32 v4, v5, v4
	v_cvt_pk_bf16_f32 v4, v4, v195
	ds_write_b16 v84, v4 offset:13360
	v_add_u32_e32 v4, v26, v83
	s_waitcnt lgkmcnt(0)
	s_barrier
; #define LAS __attribute__((address_space(3)))
; __device__ void gla_C(const Params& P, int l, int item, LAS unsigned char* lds) {
;     ...
;     __syncthreads();
; #pragma unroll
;     for (int i = 0; i < 8; ++i) { const int p = tid + i * NTHR, r = p >> 4, sg = p & 15;
;         *(u32x4*)(Z + (size_t)(row0 + r) * ZC + ZG + h * 128 + sg * 8) = *(const LAS u32x4*)(OT + r * 272 + sg * 16); }
;     __syncthreads();
	ds_read_b128 v[14:17], v4 offset:8192
	v_lshl_add_u64 v[4:5], s[28:29], 0, v[6:7]
	v_lshl_add_u64 v[4:5], v[4:5], 0, s[20:21]
	v_lshl_add_u64 v[24:25], v[4:5], 0, v[194:195]
	v_add_u32_e32 v4, v26, v82
	ds_read_b128 v[4:7], v4 offset:8192
	s_waitcnt lgkmcnt(1)
	global_store_dwordx4 v[24:25], v[14:17], off offset:2048
	v_lshl_add_u64 v[2:3], v[2:3], 0, v[194:195]
	v_mad_i64_i32 v[20:21], s[0:1], v150, s25, 0
	s_waitcnt lgkmcnt(0)
	global_store_dwordx4 v[8:9], v[4:7], off offset:2048
	v_lshl_add_u64 v[8:9], s[28:29], 0, v[10:11]
	v_lshl_add_u64 v[8:9], v[8:9], 0, s[20:21]
	v_add_u32_e32 v4, v26, v81
	ds_read_b128 v[4:7], v4 offset:8192
	v_lshl_add_u64 v[14:15], v[8:9], 0, v[194:195]
	v_add_u32_e32 v8, v26, v80
	ds_read_b128 v[8:11], v8 offset:8192
	v_mad_i64_i32 v[22:23], s[0:1], v101, s25, 0
	s_waitcnt lgkmcnt(1)
	global_store_dwordx4 v[14:15], v[4:7], off offset:2048
	s_nop 1
	v_lshl_add_u64 v[4:5], s[28:29], 0, v[12:13]
	v_lshl_add_u64 v[4:5], v[4:5], 0, s[20:21]
	v_lshl_add_u64 v[4:5], v[4:5], 0, v[194:195]
	s_waitcnt lgkmcnt(0)
	global_store_dwordx4 v[4:5], v[8:11], off offset:2048
	v_add_u32_e32 v4, v26, v79
	ds_read_b128 v[4:7], v4 offset:8192
	v_add_u32_e32 v8, v26, v78
	ds_read_b128 v[8:11], v8 offset:8192
	s_waitcnt lgkmcnt(1)
	global_store_dwordx4 v[2:3], v[4:7], off offset:2048
	v_lshl_add_u64 v[2:3], s[28:29], 0, v[18:19]
	v_lshl_add_u64 v[2:3], v[2:3], 0, s[20:21]
	v_lshl_add_u64 v[2:3], v[2:3], 0, v[194:195]
	s_waitcnt lgkmcnt(0)
	global_store_dwordx4 v[2:3], v[8:11], off offset:2048
	v_add_u32_e32 v2, v26, v77
	ds_read_b128 v[2:5], v2 offset:8192
	v_lshl_add_u64 v[6:7], s[28:29], 0, v[20:21]
	v_lshl_add_u64 v[6:7], v[6:7], 0, s[20:21]
	v_lshl_add_u64 v[10:11], v[6:7], 0, v[194:195]
	v_add_u32_e32 v6, v26, v76
	ds_read_b128 v[6:9], v6 offset:8192
	s_waitcnt lgkmcnt(1)
	global_store_dwordx4 v[10:11], v[2:5], off offset:2048
	s_nop 1
	v_lshl_add_u64 v[2:3], s[28:29], 0, v[22:23]
	v_lshl_add_u64 v[2:3], v[2:3], 0, s[20:21]
	v_lshl_add_u64 v[2:3], v[2:3], 0, v[194:195]
	s_waitcnt lgkmcnt(0)
	global_store_dwordx4 v[2:3], v[6:9], off offset:2048
	s_barrier
	s_cbranch_scc1 .LBB0_446
